# NSA final epilogue: gate/scratch loads hoisted per half with counted vmcnt waits (no store-ack stalls)
# speedup vs baseline: 1.1670x; 1.0042x over previous
; DI unsigned pk2(float a, float b) { f2_t v = {a, b}; bf2_t r = __builtin_convertvector(v, bf2_t); return __builtin_bit_cast(unsigned, r); }
; DI float bflo(unsigned u) { return (float)__builtin_bit_cast(bf2_t, u)[0]; }
; DI float bfhi(unsigned u) { return (float)__builtin_bit_cast(bf2_t, u)[1]; }
; DI float siluf_(float x) { return x / (1.f + __expf(-x)); }
; #define NSA_GATE(c_, nb_) sigmoidf_(bf2f(zb[(size_t)qpos[nb_] * ZS + GATEC + (c_) * 8 + head]))
; DI void nsa_item(const Params& p, int l_, int item, char* lds, int dry) {
;     ...
;   for (int nb = 0; nb < 2; ++nb) {
;     const float lt = l[nb] + shx(l[nb], lane, 32);
;     const float sc = ((lt > 0.f) ? 1.f / lt : 0.f) * NSA_GATE(2, nb);
;     u16* zr = zb + (size_t)qpos[nb] * ZS + GC + head * 64;
; #pragma unroll
;     for (int db = 0; db < 2; ++db)
; #pragma unroll
;       for (int a4 = 0; a4 < 4; ++a4) {
;         uint2* gp = (uint2*)(zr + db * 32 + 8 * a4 + 4 * h);
;         const uint2 gv = *gp;
;         const uint2 pv = *((const uint2*)&scr[((nb * 2 + db) * 2 + (a4 >> 1)) * 256] + (a4 & 1));
;         const unsigned o0 = pv.x, o1 = pv.y;
;         uint2 o;
;         o.x = pk2((bflo(o0) + O[db][nb][4 * a4] * sc) * siluf_(bflo(gv.x)),
;                   (bfhi(o0) + O[db][nb][4 * a4 + 1] * sc) * siluf_(bfhi(gv.x)));
;         o.y = pk2((bflo(o1) + O[db][nb][4 * a4 + 2] * sc) * siluf_(bflo(gv.y)),
;                   (bfhi(o1) + O[db][nb][4 * a4 + 3] * sc) * siluf_(bfhi(gv.y)));
;         if (dry) gp = (uint2*)&scr[((nb * 2 + db) * 2 + (a4 >> 1)) * 256] + (a4 & 1);
;         *gp = o;
;       }
.LBB0_769:
	ds_bpermute_b32 v0, v176, v2
	s_mov_b64 s[8:9], 0x2200
	s_movk_i32 s6, 0x2000
	v_mov_b32_e32 v10, v209
	v_readlane_b32 s4, v253, 1
	s_waitcnt lgkmcnt(0)
	v_add_f32_e32 v0, v2, v0
	v_div_scale_f32 v2, s[2:3], v0, v0, 1.0
	v_rcp_f32_e32 v3, v2
	v_cmp_lt_f32_e64 s[0:1], 0, v0
	v_readlane_b32 s5, v253, 2
	s_movk_i32 s2, 0x1000
	v_fma_f32 v4, -v2, v3, 1.0
	v_fmac_f32_e32 v3, v4, v3
	v_div_scale_f32 v4, vcc, 1.0, v0, 1.0
	v_mul_f32_e32 v5, v4, v3
	v_fma_f32 v6, -v2, v5, v4
	v_fmac_f32_e32 v5, v6, v3
	v_fma_f32 v2, -v2, v5, v4
	v_div_fmas_f32 v2, v2, v3, v5
	v_div_fixup_f32 v0, v2, v0, 1.0
	global_load_ushort v2, v[174:175], off offset:560
	v_cndmask_b32_e64 v0, 0, v0, s[0:1]
	v_readlane_b32 s18, v254, 21
	v_readlane_b32 s19, v254, 22
	v_readlane_b32 s31, v254, 1
	v_readlane_b32 s55, v254, 2
	s_mov_b32 s56, 0x800000
	s_movk_i32 s57, 0x104
	s_mov_b32 s58, 0xa480
	s_mov_b32 s59, 0x10000
	s_mov_b32 s74, 0xfffffc0
	s_movk_i32 s75, 0x3300
	s_mov_b32 s77, 0x378e98ab
	s_movk_i32 s97, 0x3000
	s_movk_i32 s96, 0x2000
	s_movk_i32 s79, 0x6000
	s_waitcnt vmcnt(0)
	v_cvt_f32_f16_e32 v2, v2
	v_mul_f32_e32 v2, 0xbfb8aa3b, v2
	v_exp_f32_e32 v2, v2
	s_nop 0
	v_add_f32_e32 v2, 1.0, v2
	v_div_scale_f32 v3, s[0:1], v2, v2, 1.0
	v_rcp_f32_e32 v4, v3
	s_nop 0
	v_fma_f32 v5, -v3, v4, 1.0
	v_fmac_f32_e32 v4, v5, v4
	v_div_scale_f32 v5, vcc, 1.0, v2, 1.0
	v_mul_f32_e32 v6, v5, v4
	v_fma_f32 v7, -v3, v6, v5
	v_fmac_f32_e32 v6, v7, v4
	v_fma_f32 v3, -v3, v6, v5
	v_div_fmas_f32 v3, v3, v4, v6
	v_div_fixup_f32 v2, v3, v2, 1.0
	v_mul_f32_e32 v2, v0, v2
	v_lshlrev_b32_e32 v0, 3, v177
	v_lshl_add_u64 v[6:7], v[172:173], 0, v[0:1]
	v_lshl_add_u64 v[4:5], v[6:7], 0, s[8:9]
	v_add_co_u32_e32 v6, vcc, s6, v6
	s_nop 1
	v_addc_co_u32_e32 v7, vcc, 0, v7, vcc
	global_load_dwordx2 v[8:9], v[6:7], off offset:512
	v_mov_b32_e32 v228, v209
	v_ashrrev_i32_e32 v229, 31, v228
	v_lshl_add_u64 v[228:229], v[228:229], 4, s[4:5]
	global_load_dwordx2 v[84:85], v[228:229], off
	global_load_dwordx2 v[86:87], v[4:5], off offset:16
	global_load_dwordx2 v[88:89], v[228:229], off offset:8
	global_load_dwordx2 v[90:91], v[4:5], off offset:32
	v_add_co_u32_e32 v230, vcc, 0x1000, v228
	s_nop 1
	v_addc_co_u32_e32 v231, vcc, 0, v229, vcc
	global_load_dwordx2 v[92:93], v[230:231], off
	global_load_dwordx2 v[94:95], v[4:5], off offset:48
	global_load_dwordx2 v[96:97], v[230:231], off offset:8
	global_load_dwordx2 v[98:99], v[4:5], off offset:64
	v_add_co_u32_e32 v230, vcc, 0x2000, v228
	s_nop 1
	v_addc_co_u32_e32 v231, vcc, 0, v229, vcc
	global_load_dwordx2 v[100:101], v[230:231], off
	global_load_dwordx2 v[102:103], v[4:5], off offset:80
	global_load_dwordx2 v[104:105], v[230:231], off offset:8
	global_load_dwordx2 v[106:107], v[4:5], off offset:96
	v_add_co_u32_e32 v230, vcc, 0x3000, v228
	s_nop 1
	v_addc_co_u32_e32 v231, vcc, 0, v229, vcc
	global_load_dwordx2 v[108:109], v[230:231], off
	global_load_dwordx2 v[110:111], v[4:5], off offset:112
	global_load_dwordx2 v[112:113], v[230:231], off offset:8
	s_waitcnt vmcnt(15)
	v_cvt_f32_f16_sdwa v3, v8 dst_sel:DWORD dst_unused:UNUSED_PAD src0_sel:WORD_1
	v_ashrrev_i32_e32 v11, 31, v10
	v_lshl_add_u64 v[10:11], v[10:11], 4, s[4:5]
	v_cvt_f32_f16_e32 v8, v8
	v_mul_f32_e32 v12, 0xbfb8aa3b, v8
	v_exp_f32_e32 v12, v12
	s_waitcnt vmcnt(14)
	v_cvt_f32_f16_e32 v14, v84
	v_cvt_f32_f16_sdwa v15, v84 dst_sel:DWORD dst_unused:UNUSED_PAD src0_sel:WORD_1
	v_mul_f32_e32 v10, 0xbfb8aa3b, v3
	v_exp_f32_e32 v13, v10
	v_pk_fma_f32 v[14:15], v[64:65], v[2:3], v[14:15] op_sel_hi:[1,0,1]
	v_pk_add_f32 v[12:13], v[12:13], 1.0 op_sel_hi:[1,0]
	s_nop 0
	v_div_scale_f32 v10, s[0:1], v13, v13, v3
	v_rcp_f32_e32 v64, v10
	s_nop 0
	v_fma_f32 v65, -v10, v64, 1.0
	v_fmac_f32_e32 v64, v65, v64
	v_div_scale_f32 v65, vcc, v3, v13, v3
	v_mul_f32_e32 v80, v65, v64
	v_fma_f32 v81, -v10, v80, v65
	v_fmac_f32_e32 v80, v81, v64
	v_fma_f32 v10, -v10, v80, v65
	v_div_fmas_f32 v10, v10, v64, v80
	v_div_fixup_f32 v13, v10, v13, v3
	v_div_scale_f32 v3, s[0:1], v12, v12, v8
	v_rcp_f32_e32 v10, v3
	s_nop 0
	v_fma_f32 v64, -v3, v10, 1.0
	v_fmac_f32_e32 v10, v64, v10
	v_div_scale_f32 v64, vcc, v8, v12, v8
	v_mul_f32_e32 v65, v64, v10
	v_fma_f32 v80, -v3, v65, v64
	v_fmac_f32_e32 v65, v80, v10
	v_fma_f32 v3, -v3, v65, v64
	v_div_fmas_f32 v3, v3, v10, v65
	v_div_fixup_f32 v12, v3, v12, v8
	v_cvt_f32_f16_sdwa v3, v9 dst_sel:DWORD dst_unused:UNUSED_PAD src0_sel:WORD_1
	v_cvt_f32_f16_e32 v9, v9
	v_pk_mul_f32 v[12:13], v[12:13], v[14:15]
	v_mul_f32_e32 v10, 0xbfb8aa3b, v9
	v_cvt_pk_f16_f32 v8, v12, v13
	v_cvt_f32_f16_e32 v12, v85
	v_cvt_f32_f16_sdwa v13, v85 dst_sel:DWORD dst_unused:UNUSED_PAD src0_sel:WORD_1
	v_mul_f32_e32 v11, 0xbfb8aa3b, v3
	v_exp_f32_e32 v10, v10
	v_exp_f32_e32 v11, v11
	v_pk_fma_f32 v[12:13], v[66:67], v[2:3], v[12:13] op_sel_hi:[1,0,1]
	v_pk_add_f32 v[10:11], v[10:11], 1.0 op_sel_hi:[1,0]
	s_nop 0
	v_div_scale_f32 v14, s[0:1], v11, v11, v3
	v_rcp_f32_e32 v15, v14
	s_nop 0
	v_fma_f32 v64, -v14, v15, 1.0
	v_fmac_f32_e32 v15, v64, v15
	v_div_scale_f32 v64, vcc, v3, v11, v3
	v_mul_f32_e32 v65, v64, v15
	v_fma_f32 v66, -v14, v65, v64
	v_fmac_f32_e32 v65, v66, v15
	v_fma_f32 v14, -v14, v65, v64
	v_div_fmas_f32 v14, v14, v15, v65
	v_div_fixup_f32 v11, v14, v11, v3
	v_div_scale_f32 v3, s[0:1], v10, v10, v9
	v_rcp_f32_e32 v14, v3
	s_nop 0
	v_fma_f32 v15, -v3, v14, 1.0
	v_fmac_f32_e32 v14, v15, v14
	v_div_scale_f32 v15, vcc, v9, v10, v9
	v_mul_f32_e32 v64, v15, v14
	v_fma_f32 v65, -v3, v64, v15
	v_fmac_f32_e32 v64, v65, v14
	v_fma_f32 v3, -v3, v64, v15
	v_div_fmas_f32 v3, v3, v14, v64
	v_div_fixup_f32 v10, v3, v10, v9
	v_pk_mul_f32 v[10:11], v[10:11], v[12:13]
	s_nop 0
	v_cvt_pk_f16_f32 v9, v10, v11
	global_store_dwordx2 v[6:7], v[8:9], off offset:512
	v_mov_b32_e32 v8, v209
	s_waitcnt vmcnt(14)
; DI unsigned pk2(float a, float b) { f2_t v = {a, b}; bf2_t r = __builtin_convertvector(v, bf2_t); return __builtin_bit_cast(unsigned, r); }
; DI float bflo(unsigned u) { return (float)__builtin_bit_cast(bf2_t, u)[0]; }
; DI float bfhi(unsigned u) { return (float)__builtin_bit_cast(bf2_t, u)[1]; }
; DI float siluf_(float x) { return x / (1.f + __expf(-x)); }
; #define NSA_GATE(c_, nb_) sigmoidf_(bf2f(zb[(size_t)qpos[nb_] * ZS + GATEC + (c_) * 8 + head]))
; DI void nsa_item(const Params& p, int l_, int item, char* lds, int dry) {
;     ...
;   for (int nb = 0; nb < 2; ++nb) {
;     const float lt = l[nb] + shx(l[nb], lane, 32);
;     const float sc = ((lt > 0.f) ? 1.f / lt : 0.f) * NSA_GATE(2, nb);
;     u16* zr = zb + (size_t)qpos[nb] * ZS + GC + head * 64;
; #pragma unroll
;     for (int db = 0; db < 2; ++db)
; #pragma unroll
;       for (int a4 = 0; a4 < 4; ++a4) {
;         uint2* gp = (uint2*)(zr + db * 32 + 8 * a4 + 4 * h);
;         const uint2 gv = *gp;
;         const uint2 pv = *((const uint2*)&scr[((nb * 2 + db) * 2 + (a4 >> 1)) * 256] + (a4 & 1));
;         const unsigned o0 = pv.x, o1 = pv.y;
;         uint2 o;
;         o.x = pk2((bflo(o0) + O[db][nb][4 * a4] * sc) * siluf_(bflo(gv.x)),
;                   (bfhi(o0) + O[db][nb][4 * a4 + 1] * sc) * siluf_(bfhi(gv.x)));
;         o.y = pk2((bflo(o1) + O[db][nb][4 * a4 + 2] * sc) * siluf_(bflo(gv.y)),
;                   (bfhi(o1) + O[db][nb][4 * a4 + 3] * sc) * siluf_(bfhi(gv.y)));
;         if (dry) gp = (uint2*)&scr[((nb * 2 + db) * 2 + (a4 >> 1)) * 256] + (a4 & 1);
;         *gp = o;
;       }
	v_cvt_f32_f16_sdwa v3, v86 dst_sel:DWORD dst_unused:UNUSED_PAD src0_sel:WORD_1
	v_ashrrev_i32_e32 v9, 31, v8
	v_lshl_add_u64 v[8:9], v[8:9], 4, s[4:5]
	v_cvt_f32_f16_e32 v6, v86
	v_mul_f32_e32 v10, 0xbfb8aa3b, v6
	v_exp_f32_e32 v10, v10
	s_waitcnt vmcnt(13)
	v_cvt_f32_f16_e32 v12, v88
	v_cvt_f32_f16_sdwa v13, v88 dst_sel:DWORD dst_unused:UNUSED_PAD src0_sel:WORD_1
	v_mul_f32_e32 v8, 0xbfb8aa3b, v3
	v_exp_f32_e32 v11, v8
	v_pk_fma_f32 v[12:13], v[68:69], v[2:3], v[12:13] op_sel_hi:[1,0,1]
	v_pk_add_f32 v[10:11], v[10:11], 1.0 op_sel_hi:[1,0]
	s_nop 0
	v_div_scale_f32 v8, s[0:1], v11, v11, v3
	v_rcp_f32_e32 v14, v8
	s_nop 0
	v_fma_f32 v15, -v8, v14, 1.0
	v_fmac_f32_e32 v14, v15, v14
	v_div_scale_f32 v15, vcc, v3, v11, v3
	v_mul_f32_e32 v64, v15, v14
	v_fma_f32 v65, -v8, v64, v15
	v_fmac_f32_e32 v64, v65, v14
	v_fma_f32 v8, -v8, v64, v15
	v_div_fmas_f32 v8, v8, v14, v64
	v_div_fixup_f32 v11, v8, v11, v3
	v_div_scale_f32 v3, s[0:1], v10, v10, v6
	v_rcp_f32_e32 v8, v3
	s_nop 0
	v_fma_f32 v14, -v3, v8, 1.0
	v_fmac_f32_e32 v8, v14, v8
	v_div_scale_f32 v14, vcc, v6, v10, v6
	v_mul_f32_e32 v15, v14, v8
	v_fma_f32 v64, -v3, v15, v14
	v_fmac_f32_e32 v15, v64, v8
	v_fma_f32 v3, -v3, v15, v14
	v_div_fmas_f32 v3, v3, v8, v15
	v_div_fixup_f32 v10, v3, v10, v6
	v_cvt_f32_f16_sdwa v3, v87 dst_sel:DWORD dst_unused:UNUSED_PAD src0_sel:WORD_1
	v_cvt_f32_f16_e32 v7, v87
	v_pk_mul_f32 v[10:11], v[10:11], v[12:13]
	v_mul_f32_e32 v8, 0xbfb8aa3b, v7
	v_cvt_pk_f16_f32 v6, v10, v11
	v_cvt_f32_f16_e32 v10, v89
	v_cvt_f32_f16_sdwa v11, v89 dst_sel:DWORD dst_unused:UNUSED_PAD src0_sel:WORD_1
	v_mul_f32_e32 v9, 0xbfb8aa3b, v3
	v_exp_f32_e32 v8, v8
	v_exp_f32_e32 v9, v9
	v_pk_fma_f32 v[10:11], v[70:71], v[2:3], v[10:11] op_sel_hi:[1,0,1]
	v_pk_add_f32 v[8:9], v[8:9], 1.0 op_sel_hi:[1,0]
	s_nop 0
	v_div_scale_f32 v12, s[0:1], v9, v9, v3
	v_rcp_f32_e32 v13, v12
	s_nop 0
	v_fma_f32 v14, -v12, v13, 1.0
	v_fmac_f32_e32 v13, v14, v13
	v_div_scale_f32 v14, vcc, v3, v9, v3
	v_mul_f32_e32 v15, v14, v13
	v_fma_f32 v64, -v12, v15, v14
	v_fmac_f32_e32 v15, v64, v13
	v_fma_f32 v12, -v12, v15, v14
	v_div_fmas_f32 v12, v12, v13, v15
	v_div_fixup_f32 v9, v12, v9, v3
	v_div_scale_f32 v3, s[0:1], v8, v8, v7
	v_rcp_f32_e32 v12, v3
	s_nop 0
	v_fma_f32 v13, -v3, v12, 1.0
	v_fmac_f32_e32 v12, v13, v12
	v_div_scale_f32 v13, vcc, v7, v8, v7
	v_mul_f32_e32 v14, v13, v12
	v_fma_f32 v15, -v3, v14, v13
	v_fmac_f32_e32 v14, v15, v12
	v_fma_f32 v3, -v3, v14, v13
	v_div_fmas_f32 v3, v3, v12, v14
	v_div_fixup_f32 v8, v3, v8, v7
	v_pk_mul_f32 v[8:9], v[8:9], v[10:11]
	s_nop 0
	v_cvt_pk_f16_f32 v7, v8, v9
	v_mov_b32_e32 v8, v209
	global_store_dwordx2 v[4:5], v[6:7], off offset:16
	s_waitcnt vmcnt(13)
	v_cvt_f32_f16_sdwa v3, v90 dst_sel:DWORD dst_unused:UNUSED_PAD src0_sel:WORD_1
	v_ashrrev_i32_e32 v9, 31, v8
	v_lshl_add_u64 v[8:9], v[8:9], 4, s[4:5]
	v_add_co_u32_e32 v8, vcc, s2, v8
	v_cvt_f32_f16_e32 v6, v90
	s_nop 0
	v_addc_co_u32_e32 v9, vcc, 0, v9, vcc
	v_mul_f32_e32 v10, 0xbfb8aa3b, v6
	v_exp_f32_e32 v10, v10
	s_waitcnt vmcnt(12)
	v_cvt_f32_f16_e32 v12, v92
	v_cvt_f32_f16_sdwa v13, v92 dst_sel:DWORD dst_unused:UNUSED_PAD src0_sel:WORD_1
	v_mul_f32_e32 v8, 0xbfb8aa3b, v3
	v_exp_f32_e32 v11, v8
	v_pk_fma_f32 v[12:13], v[72:73], v[2:3], v[12:13] op_sel_hi:[1,0,1]
	v_pk_add_f32 v[10:11], v[10:11], 1.0 op_sel_hi:[1,0]
	s_nop 0
	v_div_scale_f32 v8, s[0:1], v11, v11, v3
	v_rcp_f32_e32 v14, v8
	s_nop 0
	v_fma_f32 v15, -v8, v14, 1.0
	v_fmac_f32_e32 v14, v15, v14
	v_div_scale_f32 v15, vcc, v3, v11, v3
	v_mul_f32_e32 v64, v15, v14
	v_fma_f32 v65, -v8, v64, v15
	v_fmac_f32_e32 v64, v65, v14
	v_fma_f32 v8, -v8, v64, v15
	v_div_fmas_f32 v8, v8, v14, v64
	v_div_fixup_f32 v11, v8, v11, v3
	v_div_scale_f32 v3, s[0:1], v10, v10, v6
	v_rcp_f32_e32 v8, v3
	s_nop 0
	v_fma_f32 v14, -v3, v8, 1.0
	v_fmac_f32_e32 v8, v14, v8
	v_div_scale_f32 v14, vcc, v6, v10, v6
	v_mul_f32_e32 v15, v14, v8
	v_fma_f32 v64, -v3, v15, v14
	v_fmac_f32_e32 v15, v64, v8
	v_fma_f32 v3, -v3, v15, v14
	v_div_fmas_f32 v3, v3, v8, v15
	v_div_fixup_f32 v10, v3, v10, v6
	v_cvt_f32_f16_sdwa v3, v91 dst_sel:DWORD dst_unused:UNUSED_PAD src0_sel:WORD_1
	v_cvt_f32_f16_e32 v7, v91
	v_pk_mul_f32 v[10:11], v[10:11], v[12:13]
	v_mul_f32_e32 v8, 0xbfb8aa3b, v7
	v_cvt_pk_f16_f32 v6, v10, v11
	v_cvt_f32_f16_e32 v10, v93
	v_cvt_f32_f16_sdwa v11, v93 dst_sel:DWORD dst_unused:UNUSED_PAD src0_sel:WORD_1
	v_mul_f32_e32 v9, 0xbfb8aa3b, v3
	v_exp_f32_e32 v8, v8
	v_exp_f32_e32 v9, v9
	v_pk_fma_f32 v[10:11], v[74:75], v[2:3], v[10:11] op_sel_hi:[1,0,1]
	v_pk_add_f32 v[8:9], v[8:9], 1.0 op_sel_hi:[1,0]
	s_nop 0
	v_div_scale_f32 v12, s[0:1], v9, v9, v3
	v_rcp_f32_e32 v13, v12
	s_nop 0
	v_fma_f32 v14, -v12, v13, 1.0
	v_fmac_f32_e32 v13, v14, v13
	v_div_scale_f32 v14, vcc, v3, v9, v3
	v_mul_f32_e32 v15, v14, v13
	v_fma_f32 v64, -v12, v15, v14
	v_fmac_f32_e32 v15, v64, v13
	v_fma_f32 v12, -v12, v15, v14
	v_div_fmas_f32 v12, v12, v13, v15
	v_div_fixup_f32 v9, v12, v9, v3
	v_div_scale_f32 v3, s[0:1], v8, v8, v7
	v_rcp_f32_e32 v12, v3
	s_nop 0
	v_fma_f32 v13, -v3, v12, 1.0
	v_fmac_f32_e32 v12, v13, v12
	v_div_scale_f32 v13, vcc, v7, v8, v7
	v_mul_f32_e32 v14, v13, v12
	v_fma_f32 v15, -v3, v14, v13
	v_fmac_f32_e32 v14, v15, v12
	v_fma_f32 v3, -v3, v14, v13
	v_div_fmas_f32 v3, v3, v12, v14
	v_div_fixup_f32 v8, v3, v8, v7
	v_pk_mul_f32 v[8:9], v[8:9], v[10:11]
	s_nop 0
	v_cvt_pk_f16_f32 v7, v8, v9
	v_mov_b32_e32 v8, v209
	global_store_dwordx2 v[4:5], v[6:7], off offset:32
	s_waitcnt vmcnt(12)
	v_cvt_f32_f16_sdwa v3, v94 dst_sel:DWORD dst_unused:UNUSED_PAD src0_sel:WORD_1
	v_ashrrev_i32_e32 v9, 31, v8
	v_lshl_add_u64 v[8:9], v[8:9], 4, s[4:5]
	v_add_co_u32_e32 v8, vcc, s2, v8
	v_cvt_f32_f16_e32 v6, v94
	s_nop 0
	v_addc_co_u32_e32 v9, vcc, 0, v9, vcc
	v_mul_f32_e32 v10, 0xbfb8aa3b, v6
	v_exp_f32_e32 v10, v10
	s_movk_i32 s2, 0x3000
	s_waitcnt vmcnt(11)
; DI unsigned pk2(float a, float b) { f2_t v = {a, b}; bf2_t r = __builtin_convertvector(v, bf2_t); return __builtin_bit_cast(unsigned, r); }
; DI float bflo(unsigned u) { return (float)__builtin_bit_cast(bf2_t, u)[0]; }
; DI float bfhi(unsigned u) { return (float)__builtin_bit_cast(bf2_t, u)[1]; }
; DI float siluf_(float x) { return x / (1.f + __expf(-x)); }
; #define NSA_GATE(c_, nb_) sigmoidf_(bf2f(zb[(size_t)qpos[nb_] * ZS + GATEC + (c_) * 8 + head]))
; DI void nsa_item(const Params& p, int l_, int item, char* lds, int dry) {
;     ...
;   for (int nb = 0; nb < 2; ++nb) {
;     const float lt = l[nb] + shx(l[nb], lane, 32);
;     const float sc = ((lt > 0.f) ? 1.f / lt : 0.f) * NSA_GATE(2, nb);
;     u16* zr = zb + (size_t)qpos[nb] * ZS + GC + head * 64;
; #pragma unroll
;     for (int db = 0; db < 2; ++db)
; #pragma unroll
;       for (int a4 = 0; a4 < 4; ++a4) {
;         uint2* gp = (uint2*)(zr + db * 32 + 8 * a4 + 4 * h);
;         const uint2 gv = *gp;
;         const uint2 pv = *((const uint2*)&scr[((nb * 2 + db) * 2 + (a4 >> 1)) * 256] + (a4 & 1));
;         const unsigned o0 = pv.x, o1 = pv.y;
;         uint2 o;
;         o.x = pk2((bflo(o0) + O[db][nb][4 * a4] * sc) * siluf_(bflo(gv.x)),
;                   (bfhi(o0) + O[db][nb][4 * a4 + 1] * sc) * siluf_(bfhi(gv.x)));
;         o.y = pk2((bflo(o1) + O[db][nb][4 * a4 + 2] * sc) * siluf_(bflo(gv.y)),
;                   (bfhi(o1) + O[db][nb][4 * a4 + 3] * sc) * siluf_(bfhi(gv.y)));
;         if (dry) gp = (uint2*)&scr[((nb * 2 + db) * 2 + (a4 >> 1)) * 256] + (a4 & 1);
;         *gp = o;
;       }
	v_cvt_f32_f16_e32 v12, v96
	v_cvt_f32_f16_sdwa v13, v96 dst_sel:DWORD dst_unused:UNUSED_PAD src0_sel:WORD_1
	v_mul_f32_e32 v8, 0xbfb8aa3b, v3
	v_exp_f32_e32 v11, v8
	v_pk_fma_f32 v[12:13], v[76:77], v[2:3], v[12:13] op_sel_hi:[1,0,1]
	v_pk_add_f32 v[10:11], v[10:11], 1.0 op_sel_hi:[1,0]
	s_nop 0
	v_div_scale_f32 v8, s[0:1], v11, v11, v3
	v_rcp_f32_e32 v14, v8
	s_nop 0
	v_fma_f32 v15, -v8, v14, 1.0
	v_fmac_f32_e32 v14, v15, v14
	v_div_scale_f32 v15, vcc, v3, v11, v3
	v_mul_f32_e32 v64, v15, v14
	v_fma_f32 v65, -v8, v64, v15
	v_fmac_f32_e32 v64, v65, v14
	v_fma_f32 v8, -v8, v64, v15
	v_div_fmas_f32 v8, v8, v14, v64
	v_div_fixup_f32 v11, v8, v11, v3
	v_div_scale_f32 v3, s[0:1], v10, v10, v6
	v_rcp_f32_e32 v8, v3
	s_nop 0
	v_fma_f32 v14, -v3, v8, 1.0
	v_fmac_f32_e32 v8, v14, v8
	v_div_scale_f32 v14, vcc, v6, v10, v6
	v_mul_f32_e32 v15, v14, v8
	v_fma_f32 v64, -v3, v15, v14
	v_fmac_f32_e32 v15, v64, v8
	v_fma_f32 v3, -v3, v15, v14
	v_div_fmas_f32 v3, v3, v8, v15
	v_div_fixup_f32 v10, v3, v10, v6
	v_cvt_f32_f16_sdwa v3, v95 dst_sel:DWORD dst_unused:UNUSED_PAD src0_sel:WORD_1
	v_cvt_f32_f16_e32 v7, v95
	v_pk_mul_f32 v[10:11], v[10:11], v[12:13]
	v_mul_f32_e32 v8, 0xbfb8aa3b, v7
	v_cvt_pk_f16_f32 v6, v10, v11
	v_cvt_f32_f16_e32 v10, v97
	v_cvt_f32_f16_sdwa v11, v97 dst_sel:DWORD dst_unused:UNUSED_PAD src0_sel:WORD_1
	v_mul_f32_e32 v9, 0xbfb8aa3b, v3
	v_exp_f32_e32 v8, v8
	v_exp_f32_e32 v9, v9
	v_pk_fma_f32 v[10:11], v[78:79], v[2:3], v[10:11] op_sel_hi:[1,0,1]
	v_pk_add_f32 v[8:9], v[8:9], 1.0 op_sel_hi:[1,0]
	s_nop 0
	v_div_scale_f32 v12, s[0:1], v9, v9, v3
	v_rcp_f32_e32 v13, v12
	s_nop 0
	v_fma_f32 v14, -v12, v13, 1.0
	v_fmac_f32_e32 v13, v14, v13
	v_div_scale_f32 v14, vcc, v3, v9, v3
	v_mul_f32_e32 v15, v14, v13
	v_fma_f32 v64, -v12, v15, v14
	v_fmac_f32_e32 v15, v64, v13
	v_fma_f32 v12, -v12, v15, v14
	v_div_fmas_f32 v12, v12, v13, v15
	v_div_fixup_f32 v9, v12, v9, v3
	v_div_scale_f32 v3, s[0:1], v8, v8, v7
	v_rcp_f32_e32 v12, v3
	s_nop 0
	v_fma_f32 v13, -v3, v12, 1.0
	v_fmac_f32_e32 v12, v13, v12
	v_div_scale_f32 v13, vcc, v7, v8, v7
	v_mul_f32_e32 v14, v13, v12
	v_fma_f32 v15, -v3, v14, v13
	v_fmac_f32_e32 v14, v15, v12
	v_fma_f32 v3, -v3, v14, v13
	v_div_fmas_f32 v3, v3, v12, v14
	v_div_fixup_f32 v8, v3, v8, v7
	v_pk_mul_f32 v[8:9], v[8:9], v[10:11]
	s_nop 0
	v_cvt_pk_f16_f32 v7, v8, v9
	v_mov_b32_e32 v8, v209
	global_store_dwordx2 v[4:5], v[6:7], off offset:48
	s_waitcnt vmcnt(11)
	v_cvt_f32_f16_sdwa v3, v98 dst_sel:DWORD dst_unused:UNUSED_PAD src0_sel:WORD_1
	v_ashrrev_i32_e32 v9, 31, v8
	v_lshl_add_u64 v[8:9], v[8:9], 4, s[4:5]
	v_add_co_u32_e32 v8, vcc, s6, v8
	v_cvt_f32_f16_e32 v6, v98
	s_nop 0
	v_addc_co_u32_e32 v9, vcc, 0, v9, vcc
	v_mul_f32_e32 v10, 0xbfb8aa3b, v6
	v_exp_f32_e32 v10, v10
	s_waitcnt vmcnt(10)
	v_cvt_f32_f16_e32 v12, v100
	v_cvt_f32_f16_sdwa v13, v100 dst_sel:DWORD dst_unused:UNUSED_PAD src0_sel:WORD_1
	v_mul_f32_e32 v8, 0xbfb8aa3b, v3
	v_exp_f32_e32 v11, v8
	v_pk_fma_f32 v[12:13], v[48:49], v[2:3], v[12:13] op_sel_hi:[1,0,1]
	v_pk_add_f32 v[10:11], v[10:11], 1.0 op_sel_hi:[1,0]
	s_nop 0
	v_div_scale_f32 v8, s[0:1], v11, v11, v3
	v_rcp_f32_e32 v14, v8
	s_nop 0
	v_fma_f32 v15, -v8, v14, 1.0
	v_fmac_f32_e32 v14, v15, v14
	v_div_scale_f32 v15, vcc, v3, v11, v3
	v_mul_f32_e32 v48, v15, v14
	v_fma_f32 v49, -v8, v48, v15
	v_fmac_f32_e32 v48, v49, v14
	v_fma_f32 v8, -v8, v48, v15
	v_div_fmas_f32 v8, v8, v14, v48
	v_div_fixup_f32 v11, v8, v11, v3
	v_div_scale_f32 v3, s[0:1], v10, v10, v6
	v_rcp_f32_e32 v8, v3
	s_nop 0
	v_fma_f32 v14, -v3, v8, 1.0
	v_fmac_f32_e32 v8, v14, v8
	v_div_scale_f32 v14, vcc, v6, v10, v6
	v_mul_f32_e32 v15, v14, v8
	v_fma_f32 v48, -v3, v15, v14
	v_fmac_f32_e32 v15, v48, v8
	v_fma_f32 v3, -v3, v15, v14
	v_div_fmas_f32 v3, v3, v8, v15
	v_div_fixup_f32 v10, v3, v10, v6
	v_cvt_f32_f16_sdwa v3, v99 dst_sel:DWORD dst_unused:UNUSED_PAD src0_sel:WORD_1
	v_cvt_f32_f16_e32 v7, v99
	v_pk_mul_f32 v[10:11], v[10:11], v[12:13]
	v_mul_f32_e32 v8, 0xbfb8aa3b, v7
	v_cvt_pk_f16_f32 v6, v10, v11
	v_cvt_f32_f16_e32 v10, v101
	v_cvt_f32_f16_sdwa v11, v101 dst_sel:DWORD dst_unused:UNUSED_PAD src0_sel:WORD_1
	v_mul_f32_e32 v9, 0xbfb8aa3b, v3
	v_exp_f32_e32 v8, v8
	v_exp_f32_e32 v9, v9
	v_pk_fma_f32 v[10:11], v[50:51], v[2:3], v[10:11] op_sel_hi:[1,0,1]
	v_pk_add_f32 v[8:9], v[8:9], 1.0 op_sel_hi:[1,0]
	s_nop 0
	v_div_scale_f32 v12, s[0:1], v9, v9, v3
	v_rcp_f32_e32 v13, v12
	s_nop 0
	v_fma_f32 v14, -v12, v13, 1.0
	v_fmac_f32_e32 v13, v14, v13
	v_div_scale_f32 v14, vcc, v3, v9, v3
	v_mul_f32_e32 v15, v14, v13
	v_fma_f32 v48, -v12, v15, v14
	v_fmac_f32_e32 v15, v48, v13
	v_fma_f32 v12, -v12, v15, v14
	v_div_fmas_f32 v12, v12, v13, v15
	v_div_fixup_f32 v9, v12, v9, v3
	v_div_scale_f32 v3, s[0:1], v8, v8, v7
	v_rcp_f32_e32 v12, v3
	s_nop 0
	v_fma_f32 v13, -v3, v12, 1.0
	v_fmac_f32_e32 v12, v13, v12
	v_div_scale_f32 v13, vcc, v7, v8, v7
	v_mul_f32_e32 v14, v13, v12
	v_fma_f32 v15, -v3, v14, v13
	v_fmac_f32_e32 v14, v15, v12
	v_fma_f32 v3, -v3, v14, v13
	v_div_fmas_f32 v3, v3, v12, v14
	v_div_fixup_f32 v8, v3, v8, v7
	v_pk_mul_f32 v[8:9], v[8:9], v[10:11]
	s_nop 0
	v_cvt_pk_f16_f32 v7, v8, v9
	v_mov_b32_e32 v8, v209
	global_store_dwordx2 v[4:5], v[6:7], off offset:64
	s_waitcnt vmcnt(10)
	v_cvt_f32_f16_sdwa v3, v102 dst_sel:DWORD dst_unused:UNUSED_PAD src0_sel:WORD_1
	v_ashrrev_i32_e32 v9, 31, v8
	v_lshl_add_u64 v[8:9], v[8:9], 4, s[4:5]
	v_add_co_u32_e32 v8, vcc, s6, v8
	v_cvt_f32_f16_e32 v6, v102
	s_nop 0
	v_addc_co_u32_e32 v9, vcc, 0, v9, vcc
	v_mul_f32_e32 v10, 0xbfb8aa3b, v6
	v_exp_f32_e32 v10, v10
	s_waitcnt vmcnt(9)
; DI unsigned pk2(float a, float b) { f2_t v = {a, b}; bf2_t r = __builtin_convertvector(v, bf2_t); return __builtin_bit_cast(unsigned, r); }
; DI float bflo(unsigned u) { return (float)__builtin_bit_cast(bf2_t, u)[0]; }
; DI float bfhi(unsigned u) { return (float)__builtin_bit_cast(bf2_t, u)[1]; }
; DI float siluf_(float x) { return x / (1.f + __expf(-x)); }
; #define NSA_GATE(c_, nb_) sigmoidf_(bf2f(zb[(size_t)qpos[nb_] * ZS + GATEC + (c_) * 8 + head]))
; DI void nsa_item(const Params& p, int l_, int item, char* lds, int dry) {
;     ...
;   for (int nb = 0; nb < 2; ++nb) {
;     const float lt = l[nb] + shx(l[nb], lane, 32);
;     const float sc = ((lt > 0.f) ? 1.f / lt : 0.f) * NSA_GATE(2, nb);
;     u16* zr = zb + (size_t)qpos[nb] * ZS + GC + head * 64;
; #pragma unroll
;     for (int db = 0; db < 2; ++db)
; #pragma unroll
;       for (int a4 = 0; a4 < 4; ++a4) {
;         uint2* gp = (uint2*)(zr + db * 32 + 8 * a4 + 4 * h);
;         const uint2 gv = *gp;
;         const uint2 pv = *((const uint2*)&scr[((nb * 2 + db) * 2 + (a4 >> 1)) * 256] + (a4 & 1));
;         const unsigned o0 = pv.x, o1 = pv.y;
;         uint2 o;
;         o.x = pk2((bflo(o0) + O[db][nb][4 * a4] * sc) * siluf_(bflo(gv.x)),
;                   (bfhi(o0) + O[db][nb][4 * a4 + 1] * sc) * siluf_(bfhi(gv.x)));
;         o.y = pk2((bflo(o1) + O[db][nb][4 * a4 + 2] * sc) * siluf_(bflo(gv.y)),
;                   (bfhi(o1) + O[db][nb][4 * a4 + 3] * sc) * siluf_(bfhi(gv.y)));
;         if (dry) gp = (uint2*)&scr[((nb * 2 + db) * 2 + (a4 >> 1)) * 256] + (a4 & 1);
;         *gp = o;
;       }
	v_cvt_f32_f16_e32 v12, v104
	v_cvt_f32_f16_sdwa v13, v104 dst_sel:DWORD dst_unused:UNUSED_PAD src0_sel:WORD_1
	v_mul_f32_e32 v8, 0xbfb8aa3b, v3
	v_exp_f32_e32 v11, v8
	v_pk_fma_f32 v[12:13], v[52:53], v[2:3], v[12:13] op_sel_hi:[1,0,1]
	v_pk_add_f32 v[10:11], v[10:11], 1.0 op_sel_hi:[1,0]
	s_nop 0
	v_div_scale_f32 v8, s[0:1], v11, v11, v3
	v_rcp_f32_e32 v14, v8
	s_nop 0
	v_fma_f32 v15, -v8, v14, 1.0
	v_fmac_f32_e32 v14, v15, v14
	v_div_scale_f32 v15, vcc, v3, v11, v3
	v_mul_f32_e32 v48, v15, v14
	v_fma_f32 v49, -v8, v48, v15
	v_fmac_f32_e32 v48, v49, v14
	v_fma_f32 v8, -v8, v48, v15
	v_div_fmas_f32 v8, v8, v14, v48
	v_div_fixup_f32 v11, v8, v11, v3
	v_div_scale_f32 v3, s[0:1], v10, v10, v6
	v_rcp_f32_e32 v8, v3
	s_nop 0
	v_fma_f32 v14, -v3, v8, 1.0
	v_fmac_f32_e32 v8, v14, v8
	v_div_scale_f32 v14, vcc, v6, v10, v6
	v_mul_f32_e32 v15, v14, v8
	v_fma_f32 v48, -v3, v15, v14
	v_fmac_f32_e32 v15, v48, v8
	v_fma_f32 v3, -v3, v15, v14
	v_div_fmas_f32 v3, v3, v8, v15
	v_div_fixup_f32 v10, v3, v10, v6
	v_cvt_f32_f16_sdwa v3, v103 dst_sel:DWORD dst_unused:UNUSED_PAD src0_sel:WORD_1
	v_cvt_f32_f16_e32 v7, v103
	v_pk_mul_f32 v[10:11], v[10:11], v[12:13]
	v_mul_f32_e32 v8, 0xbfb8aa3b, v7
	v_cvt_pk_f16_f32 v6, v10, v11
	v_cvt_f32_f16_e32 v10, v105
	v_cvt_f32_f16_sdwa v11, v105 dst_sel:DWORD dst_unused:UNUSED_PAD src0_sel:WORD_1
	v_mul_f32_e32 v9, 0xbfb8aa3b, v3
	v_exp_f32_e32 v8, v8
	v_exp_f32_e32 v9, v9
	v_pk_fma_f32 v[10:11], v[54:55], v[2:3], v[10:11] op_sel_hi:[1,0,1]
	v_pk_add_f32 v[8:9], v[8:9], 1.0 op_sel_hi:[1,0]
	s_nop 0
	v_div_scale_f32 v12, s[0:1], v9, v9, v3
	v_rcp_f32_e32 v13, v12
	s_nop 0
	v_fma_f32 v14, -v12, v13, 1.0
	v_fmac_f32_e32 v13, v14, v13
	v_div_scale_f32 v14, vcc, v3, v9, v3
	v_mul_f32_e32 v15, v14, v13
	v_fma_f32 v48, -v12, v15, v14
	v_fmac_f32_e32 v15, v48, v13
	v_fma_f32 v12, -v12, v15, v14
	v_div_fmas_f32 v12, v12, v13, v15
	v_div_fixup_f32 v9, v12, v9, v3
	v_div_scale_f32 v3, s[0:1], v8, v8, v7
	v_rcp_f32_e32 v12, v3
	s_nop 0
	v_fma_f32 v13, -v3, v12, 1.0
	v_fmac_f32_e32 v12, v13, v12
	v_div_scale_f32 v13, vcc, v7, v8, v7
	v_mul_f32_e32 v14, v13, v12
	v_fma_f32 v15, -v3, v14, v13
	v_fmac_f32_e32 v14, v15, v12
	v_fma_f32 v3, -v3, v14, v13
	v_div_fmas_f32 v3, v3, v12, v14
	v_div_fixup_f32 v8, v3, v8, v7
	v_pk_mul_f32 v[8:9], v[8:9], v[10:11]
	s_nop 0
	v_cvt_pk_f16_f32 v7, v8, v9
	v_mov_b32_e32 v8, v209
	global_store_dwordx2 v[4:5], v[6:7], off offset:80
	s_waitcnt vmcnt(9)
	v_cvt_f32_f16_sdwa v3, v106 dst_sel:DWORD dst_unused:UNUSED_PAD src0_sel:WORD_1
	v_ashrrev_i32_e32 v9, 31, v8
	v_lshl_add_u64 v[8:9], v[8:9], 4, s[4:5]
	v_add_co_u32_e32 v8, vcc, s2, v8
	v_cvt_f32_f16_e32 v6, v106
	s_nop 0
	v_addc_co_u32_e32 v9, vcc, 0, v9, vcc
	v_mul_f32_e32 v10, 0xbfb8aa3b, v6
	v_exp_f32_e32 v10, v10
	s_waitcnt vmcnt(8)
	v_cvt_f32_f16_e32 v12, v108
	v_cvt_f32_f16_sdwa v13, v108 dst_sel:DWORD dst_unused:UNUSED_PAD src0_sel:WORD_1
	v_mul_f32_e32 v8, 0xbfb8aa3b, v3
	v_exp_f32_e32 v11, v8
	v_pk_fma_f32 v[12:13], v[56:57], v[2:3], v[12:13] op_sel_hi:[1,0,1]
	v_pk_add_f32 v[10:11], v[10:11], 1.0 op_sel_hi:[1,0]
	s_nop 0
	v_div_scale_f32 v8, s[0:1], v11, v11, v3
	v_rcp_f32_e32 v14, v8
	s_nop 0
	v_fma_f32 v15, -v8, v14, 1.0
	v_fmac_f32_e32 v14, v15, v14
	v_div_scale_f32 v15, vcc, v3, v11, v3
	v_mul_f32_e32 v48, v15, v14
	v_fma_f32 v49, -v8, v48, v15
	v_fmac_f32_e32 v48, v49, v14
	v_fma_f32 v8, -v8, v48, v15
	v_div_fmas_f32 v8, v8, v14, v48
	v_div_fixup_f32 v11, v8, v11, v3
	v_div_scale_f32 v3, s[0:1], v10, v10, v6
	v_rcp_f32_e32 v8, v3
	s_nop 0
	v_fma_f32 v14, -v3, v8, 1.0
	v_fmac_f32_e32 v8, v14, v8
	v_div_scale_f32 v14, vcc, v6, v10, v6
	v_mul_f32_e32 v15, v14, v8
	v_fma_f32 v48, -v3, v15, v14
	v_fmac_f32_e32 v15, v48, v8
	v_fma_f32 v3, -v3, v15, v14
	v_div_fmas_f32 v3, v3, v8, v15
	v_div_fixup_f32 v10, v3, v10, v6
	v_cvt_f32_f16_sdwa v3, v107 dst_sel:DWORD dst_unused:UNUSED_PAD src0_sel:WORD_1
	v_cvt_f32_f16_e32 v7, v107
	v_pk_mul_f32 v[10:11], v[10:11], v[12:13]
	v_mul_f32_e32 v8, 0xbfb8aa3b, v7
	v_cvt_pk_f16_f32 v6, v10, v11
	v_cvt_f32_f16_e32 v10, v109
	v_cvt_f32_f16_sdwa v11, v109 dst_sel:DWORD dst_unused:UNUSED_PAD src0_sel:WORD_1
	v_mul_f32_e32 v9, 0xbfb8aa3b, v3
	v_exp_f32_e32 v8, v8
	v_exp_f32_e32 v9, v9
	v_pk_fma_f32 v[10:11], v[58:59], v[2:3], v[10:11] op_sel_hi:[1,0,1]
	v_pk_add_f32 v[8:9], v[8:9], 1.0 op_sel_hi:[1,0]
	s_nop 0
	v_div_scale_f32 v12, s[0:1], v9, v9, v3
	v_rcp_f32_e32 v13, v12
	s_nop 0
	v_fma_f32 v14, -v12, v13, 1.0
	v_fmac_f32_e32 v13, v14, v13
	v_div_scale_f32 v14, vcc, v3, v9, v3
	v_mul_f32_e32 v15, v14, v13
	v_fma_f32 v48, -v12, v15, v14
	v_fmac_f32_e32 v15, v48, v13
	v_fma_f32 v12, -v12, v15, v14
	v_div_fmas_f32 v12, v12, v13, v15
	v_div_fixup_f32 v9, v12, v9, v3
	v_div_scale_f32 v3, s[0:1], v8, v8, v7
	v_rcp_f32_e32 v12, v3
	s_nop 0
	v_fma_f32 v13, -v3, v12, 1.0
	v_fmac_f32_e32 v12, v13, v12
	v_div_scale_f32 v13, vcc, v7, v8, v7
	v_mul_f32_e32 v14, v13, v12
	v_fma_f32 v15, -v3, v14, v13
	v_fmac_f32_e32 v14, v15, v12
	v_fma_f32 v3, -v3, v14, v13
	v_div_fmas_f32 v3, v3, v12, v14
	v_div_fixup_f32 v8, v3, v8, v7
	v_pk_mul_f32 v[8:9], v[8:9], v[10:11]
	s_nop 0
	v_cvt_pk_f16_f32 v7, v8, v9
	v_mov_b32_e32 v8, v209
	global_store_dwordx2 v[4:5], v[6:7], off offset:96
	s_waitcnt vmcnt(8)
	v_cvt_f32_f16_sdwa v3, v110 dst_sel:DWORD dst_unused:UNUSED_PAD src0_sel:WORD_1
	v_ashrrev_i32_e32 v9, 31, v8
	v_lshl_add_u64 v[8:9], v[8:9], 4, s[4:5]
	v_add_co_u32_e32 v8, vcc, s2, v8
	v_cvt_f32_f16_e32 v6, v110
	s_nop 0
	v_addc_co_u32_e32 v9, vcc, 0, v9, vcc
	v_mul_f32_e32 v10, 0xbfb8aa3b, v6
	v_exp_f32_e32 v10, v10
	s_waitcnt vmcnt(7)
; DI unsigned pk2(float a, float b) { f2_t v = {a, b}; bf2_t r = __builtin_convertvector(v, bf2_t); return __builtin_bit_cast(unsigned, r); }
; DI float bflo(unsigned u) { return (float)__builtin_bit_cast(bf2_t, u)[0]; }
; DI float bfhi(unsigned u) { return (float)__builtin_bit_cast(bf2_t, u)[1]; }
; DI float siluf_(float x) { return x / (1.f + __expf(-x)); }
; #define NSA_GATE(c_, nb_) sigmoidf_(bf2f(zb[(size_t)qpos[nb_] * ZS + GATEC + (c_) * 8 + head]))
; DI void nsa_item(const Params& p, int l_, int item, char* lds, int dry) {
;     ...
;   for (int nb = 0; nb < 2; ++nb) {
;     const float lt = l[nb] + shx(l[nb], lane, 32);
;     const float sc = ((lt > 0.f) ? 1.f / lt : 0.f) * NSA_GATE(2, nb);
;     u16* zr = zb + (size_t)qpos[nb] * ZS + GC + head * 64;
; #pragma unroll
;     for (int db = 0; db < 2; ++db)
; #pragma unroll
;       for (int a4 = 0; a4 < 4; ++a4) {
;         uint2* gp = (uint2*)(zr + db * 32 + 8 * a4 + 4 * h);
;         const uint2 gv = *gp;
;         const uint2 pv = *((const uint2*)&scr[((nb * 2 + db) * 2 + (a4 >> 1)) * 256] + (a4 & 1));
;         const unsigned o0 = pv.x, o1 = pv.y;
;         uint2 o;
;         o.x = pk2((bflo(o0) + O[db][nb][4 * a4] * sc) * siluf_(bflo(gv.x)),
;                   (bfhi(o0) + O[db][nb][4 * a4 + 1] * sc) * siluf_(bfhi(gv.x)));
;         o.y = pk2((bflo(o1) + O[db][nb][4 * a4 + 2] * sc) * siluf_(bflo(gv.y)),
;                   (bfhi(o1) + O[db][nb][4 * a4 + 3] * sc) * siluf_(bfhi(gv.y)));
;         if (dry) gp = (uint2*)&scr[((nb * 2 + db) * 2 + (a4 >> 1)) * 256] + (a4 & 1);
;         *gp = o;
;       }
	v_cvt_f32_f16_e32 v12, v112
	v_cvt_f32_f16_sdwa v13, v112 dst_sel:DWORD dst_unused:UNUSED_PAD src0_sel:WORD_1
	v_mul_f32_e32 v8, 0xbfb8aa3b, v3
	v_exp_f32_e32 v11, v8
	v_pk_fma_f32 v[12:13], v[60:61], v[2:3], v[12:13] op_sel_hi:[1,0,1]
	v_pk_add_f32 v[10:11], v[10:11], 1.0 op_sel_hi:[1,0]
	s_nop 0
	v_div_scale_f32 v8, s[0:1], v11, v11, v3
	v_rcp_f32_e32 v14, v8
	s_nop 0
	v_fma_f32 v15, -v8, v14, 1.0
	v_fmac_f32_e32 v14, v15, v14
	v_div_scale_f32 v15, vcc, v3, v11, v3
	v_mul_f32_e32 v48, v15, v14
	v_fma_f32 v49, -v8, v48, v15
	v_fmac_f32_e32 v48, v49, v14
	v_fma_f32 v8, -v8, v48, v15
	v_div_fmas_f32 v8, v8, v14, v48
	v_div_fixup_f32 v11, v8, v11, v3
	v_div_scale_f32 v3, s[0:1], v10, v10, v6
	v_rcp_f32_e32 v8, v3
	s_nop 0
	v_fma_f32 v14, -v3, v8, 1.0
	v_fmac_f32_e32 v8, v14, v8
	v_div_scale_f32 v14, vcc, v6, v10, v6
	v_mul_f32_e32 v15, v14, v8
	v_fma_f32 v48, -v3, v15, v14
	v_fmac_f32_e32 v15, v48, v8
	v_fma_f32 v3, -v3, v15, v14
	v_div_fmas_f32 v3, v3, v8, v15
	v_div_fixup_f32 v10, v3, v10, v6
	v_pk_mul_f32 v[10:11], v[10:11], v[12:13]
	v_cvt_f32_f16_sdwa v12, v111 dst_sel:DWORD dst_unused:UNUSED_PAD src0_sel:WORD_1
	v_cvt_f32_f16_e32 v7, v111
	v_cvt_pk_f16_f32 v6, v10, v11
	v_cvt_f32_f16_e32 v10, v113
	v_cvt_f32_f16_sdwa v11, v113 dst_sel:DWORD dst_unused:UNUSED_PAD src0_sel:WORD_1
	v_mul_f32_e32 v3, 0xbfb8aa3b, v7
	v_mul_f32_e32 v9, 0xbfb8aa3b, v12
	v_exp_f32_e32 v8, v3
	v_exp_f32_e32 v9, v9
	v_pk_fma_f32 v[2:3], v[62:63], v[2:3], v[10:11] op_sel_hi:[1,0,1]
	v_pk_add_f32 v[8:9], v[8:9], 1.0 op_sel_hi:[1,0]
	s_nop 0
	v_div_scale_f32 v10, s[0:1], v9, v9, v12
	v_rcp_f32_e32 v11, v10
	s_nop 0
	v_fma_f32 v13, -v10, v11, 1.0
	v_fmac_f32_e32 v11, v13, v11
	v_div_scale_f32 v13, vcc, v12, v9, v12
	v_mul_f32_e32 v14, v13, v11
	v_fma_f32 v15, -v10, v14, v13
	v_fmac_f32_e32 v14, v15, v11
	v_fma_f32 v10, -v10, v14, v13
	v_div_fmas_f32 v10, v10, v11, v14
	v_div_fixup_f32 v9, v10, v9, v12
	v_div_scale_f32 v10, s[0:1], v8, v8, v7
	v_rcp_f32_e32 v11, v10
	s_nop 0
	v_fma_f32 v12, -v10, v11, 1.0
	v_fmac_f32_e32 v11, v12, v11
	v_div_scale_f32 v12, vcc, v7, v8, v7
	v_mul_f32_e32 v13, v12, v11
	v_fma_f32 v14, -v10, v13, v12
	v_fmac_f32_e32 v13, v14, v11
	v_fma_f32 v10, -v10, v13, v12
	v_div_fmas_f32 v10, v10, v11, v13
	v_div_fixup_f32 v8, v10, v8, v7
	v_pk_mul_f32 v[2:3], v[8:9], v[2:3]
	v_mov_b32_e32 v10, v209
	v_cvt_pk_f16_f32 v7, v2, v3
	ds_bpermute_b32 v2, v176, v164
	global_store_dwordx2 v[4:5], v[6:7], off offset:112
	s_waitcnt lgkmcnt(0)
	v_add_f32_e32 v2, v164, v2
	v_div_scale_f32 v3, s[2:3], v2, v2, 1.0
	v_rcp_f32_e32 v4, v3
	v_cmp_lt_f32_e64 s[0:1], 0, v2
	s_movk_i32 s2, 0x4000
	v_fma_f32 v5, -v3, v4, 1.0
	v_fmac_f32_e32 v4, v5, v4
	v_div_scale_f32 v5, vcc, 1.0, v2, 1.0
	v_mul_f32_e32 v6, v5, v4
	v_fma_f32 v7, -v3, v6, v5
	v_fmac_f32_e32 v6, v7, v4
	v_fma_f32 v3, -v3, v6, v5
	v_div_fmas_f32 v3, v3, v4, v6
	v_div_fixup_f32 v2, v3, v2, 1.0
	global_load_ushort v3, v[170:171], off offset:560
	v_cndmask_b32_e64 v2, 0, v2, s[0:1]
	s_waitcnt vmcnt(0)
	v_cvt_f32_f16_e32 v3, v3
	v_mul_f32_e32 v3, 0xbfb8aa3b, v3
	v_exp_f32_e32 v3, v3
	s_nop 0
	v_add_f32_e32 v3, 1.0, v3
	v_div_scale_f32 v4, s[0:1], v3, v3, 1.0
	v_rcp_f32_e32 v5, v4
	s_nop 0
	v_fma_f32 v6, -v4, v5, 1.0
	v_fmac_f32_e32 v5, v6, v5
	v_div_scale_f32 v6, vcc, 1.0, v3, 1.0
	v_mul_f32_e32 v7, v6, v5
	v_fma_f32 v8, -v4, v7, v6
	v_fmac_f32_e32 v7, v8, v5
	v_fma_f32 v4, -v4, v7, v6
	v_div_fmas_f32 v4, v4, v5, v7
	v_lshl_add_u64 v[6:7], v[168:169], 0, v[0:1]
	v_div_fixup_f32 v3, v4, v3, 1.0
	v_lshl_add_u64 v[4:5], v[6:7], 0, s[8:9]
	v_add_co_u32_e32 v6, vcc, s6, v6
	v_mul_f32_e32 v2, v2, v3
	s_nop 0
	v_addc_co_u32_e32 v7, vcc, 0, v7, vcc
	global_load_dwordx2 v[8:9], v[6:7], off offset:512
	v_mov_b32_e32 v228, v209
	v_ashrrev_i32_e32 v229, 31, v228
	v_lshl_add_u64 v[228:229], v[228:229], 4, s[4:5]
	v_add_co_u32_e32 v230, vcc, 0x4000, v228
	s_nop 1
	v_addc_co_u32_e32 v231, vcc, 0, v229, vcc
	global_load_dwordx2 v[84:85], v[230:231], off
	global_load_dwordx2 v[86:87], v[4:5], off offset:16
	global_load_dwordx2 v[88:89], v[230:231], off offset:8
	global_load_dwordx2 v[90:91], v[4:5], off offset:32
	v_add_co_u32_e32 v230, vcc, 0x5000, v228
	s_nop 1
	v_addc_co_u32_e32 v231, vcc, 0, v229, vcc
	global_load_dwordx2 v[92:93], v[230:231], off
	global_load_dwordx2 v[94:95], v[4:5], off offset:48
	global_load_dwordx2 v[96:97], v[230:231], off offset:8
	global_load_dwordx2 v[98:99], v[4:5], off offset:64
	v_add_co_u32_e32 v230, vcc, 0x6000, v228
	s_nop 1
	v_addc_co_u32_e32 v231, vcc, 0, v229, vcc
	global_load_dwordx2 v[100:101], v[230:231], off
	global_load_dwordx2 v[102:103], v[4:5], off offset:80
	global_load_dwordx2 v[104:105], v[230:231], off offset:8
	global_load_dwordx2 v[106:107], v[4:5], off offset:96
	v_add_co_u32_e32 v230, vcc, 0x7000, v228
	s_nop 1
	v_addc_co_u32_e32 v231, vcc, 0, v229, vcc
	global_load_dwordx2 v[108:109], v[230:231], off
	global_load_dwordx2 v[110:111], v[4:5], off offset:112
	global_load_dwordx2 v[112:113], v[230:231], off offset:8
	s_waitcnt vmcnt(15)
	v_cvt_f32_f16_e32 v3, v8
	v_ashrrev_i32_e32 v11, 31, v10
	v_lshl_add_u64 v[10:11], v[10:11], 4, s[4:5]
	v_add_co_u32_e32 v10, vcc, s2, v10
	v_cvt_f32_f16_sdwa v0, v8 dst_sel:DWORD dst_unused:UNUSED_PAD src0_sel:WORD_1
	s_nop 0
	v_addc_co_u32_e32 v11, vcc, 0, v11, vcc
	v_mul_f32_e32 v8, 0xbfb8aa3b, v3
	v_exp_f32_e32 v12, v8
	v_mul_f32_e32 v8, 0xbfb8aa3b, v0
	v_exp_f32_e32 v13, v8
	s_waitcnt vmcnt(14)
; DI unsigned pk2(float a, float b) { f2_t v = {a, b}; bf2_t r = __builtin_convertvector(v, bf2_t); return __builtin_bit_cast(unsigned, r); }
; DI float bflo(unsigned u) { return (float)__builtin_bit_cast(bf2_t, u)[0]; }
; DI float bfhi(unsigned u) { return (float)__builtin_bit_cast(bf2_t, u)[1]; }
; DI float siluf_(float x) { return x / (1.f + __expf(-x)); }
; #define NSA_GATE(c_, nb_) sigmoidf_(bf2f(zb[(size_t)qpos[nb_] * ZS + GATEC + (c_) * 8 + head]))
; DI void nsa_item(const Params& p, int l_, int item, char* lds, int dry) {
;     ...
;   for (int nb = 0; nb < 2; ++nb) {
;     const float lt = l[nb] + shx(l[nb], lane, 32);
;     const float sc = ((lt > 0.f) ? 1.f / lt : 0.f) * NSA_GATE(2, nb);
;     u16* zr = zb + (size_t)qpos[nb] * ZS + GC + head * 64;
; #pragma unroll
;     for (int db = 0; db < 2; ++db)
; #pragma unroll
;       for (int a4 = 0; a4 < 4; ++a4) {
;         uint2* gp = (uint2*)(zr + db * 32 + 8 * a4 + 4 * h);
;         const uint2 gv = *gp;
;         const uint2 pv = *((const uint2*)&scr[((nb * 2 + db) * 2 + (a4 >> 1)) * 256] + (a4 & 1));
;         const unsigned o0 = pv.x, o1 = pv.y;
;         uint2 o;
;         o.x = pk2((bflo(o0) + O[db][nb][4 * a4] * sc) * siluf_(bflo(gv.x)),
;                   (bfhi(o0) + O[db][nb][4 * a4 + 1] * sc) * siluf_(bfhi(gv.x)));
;         o.y = pk2((bflo(o1) + O[db][nb][4 * a4 + 2] * sc) * siluf_(bflo(gv.y)),
;                   (bfhi(o1) + O[db][nb][4 * a4 + 3] * sc) * siluf_(bfhi(gv.y)));
;         if (dry) gp = (uint2*)&scr[((nb * 2 + db) * 2 + (a4 >> 1)) * 256] + (a4 & 1);
;         *gp = o;
;       }
	v_cvt_f32_f16_e32 v14, v84
	v_pk_add_f32 v[12:13], v[12:13], 1.0 op_sel_hi:[1,0]
	v_cvt_f32_f16_sdwa v15, v84 dst_sel:DWORD dst_unused:UNUSED_PAD src0_sel:WORD_1
	v_div_scale_f32 v8, s[0:1], v13, v13, v0
	v_rcp_f32_e32 v10, v8
	v_pk_fma_f32 v[14:15], v[32:33], v[2:3], v[14:15] op_sel_hi:[1,0,1]
	v_fma_f32 v32, -v8, v10, 1.0
	v_fmac_f32_e32 v10, v32, v10
	v_div_scale_f32 v32, vcc, v0, v13, v0
	v_mul_f32_e32 v33, v32, v10
	v_fma_f32 v48, -v8, v33, v32
	v_fmac_f32_e32 v33, v48, v10
	v_fma_f32 v8, -v8, v33, v32
	v_div_fmas_f32 v8, v8, v10, v33
	v_div_fixup_f32 v13, v8, v13, v0
	v_div_scale_f32 v0, s[0:1], v12, v12, v3
	v_rcp_f32_e32 v8, v0
	s_nop 0
	v_fma_f32 v10, -v0, v8, 1.0
	v_fmac_f32_e32 v8, v10, v8
	v_div_scale_f32 v10, vcc, v3, v12, v3
	v_mul_f32_e32 v32, v10, v8
	v_fma_f32 v33, -v0, v32, v10
	v_fmac_f32_e32 v32, v33, v8
	v_fma_f32 v0, -v0, v32, v10
	v_div_fmas_f32 v0, v0, v8, v32
	v_div_fixup_f32 v12, v0, v12, v3
	v_cvt_f32_f16_e32 v3, v9
	v_cvt_f32_f16_sdwa v0, v9 dst_sel:DWORD dst_unused:UNUSED_PAD src0_sel:WORD_1
	v_pk_mul_f32 v[12:13], v[12:13], v[14:15]
	v_mul_f32_e32 v9, 0xbfb8aa3b, v3
	v_exp_f32_e32 v10, v9
	v_mul_f32_e32 v9, 0xbfb8aa3b, v0
	v_cvt_pk_f16_f32 v8, v12, v13
	v_cvt_f32_f16_e32 v12, v85
	v_cvt_f32_f16_sdwa v13, v85 dst_sel:DWORD dst_unused:UNUSED_PAD src0_sel:WORD_1
	v_exp_f32_e32 v11, v9
	v_pk_fma_f32 v[12:13], v[34:35], v[2:3], v[12:13] op_sel_hi:[1,0,1]
	v_pk_add_f32 v[10:11], v[10:11], 1.0 op_sel_hi:[1,0]
	s_nop 0
	v_div_scale_f32 v9, s[0:1], v11, v11, v0
	v_rcp_f32_e32 v14, v9
	s_nop 0
	v_fma_f32 v15, -v9, v14, 1.0
	v_fmac_f32_e32 v14, v15, v14
	v_div_scale_f32 v15, vcc, v0, v11, v0
	v_mul_f32_e32 v32, v15, v14
	v_fma_f32 v33, -v9, v32, v15
	v_fmac_f32_e32 v32, v33, v14
	v_fma_f32 v9, -v9, v32, v15
	v_div_fmas_f32 v9, v9, v14, v32
	v_div_fixup_f32 v11, v9, v11, v0
	v_div_scale_f32 v0, s[0:1], v10, v10, v3
	v_rcp_f32_e32 v9, v0
	s_nop 0
	v_fma_f32 v14, -v0, v9, 1.0
	v_fmac_f32_e32 v9, v14, v9
	v_div_scale_f32 v14, vcc, v3, v10, v3
	v_mul_f32_e32 v15, v14, v9
	v_fma_f32 v32, -v0, v15, v14
	v_fmac_f32_e32 v15, v32, v9
	v_fma_f32 v0, -v0, v15, v14
	v_div_fmas_f32 v0, v0, v9, v15
	v_div_fixup_f32 v10, v0, v10, v3
	v_pk_mul_f32 v[10:11], v[10:11], v[12:13]
	s_nop 0
	v_cvt_pk_f16_f32 v9, v10, v11
	global_store_dwordx2 v[6:7], v[8:9], off offset:512
	v_mov_b32_e32 v8, v209
	s_waitcnt vmcnt(14)
	v_cvt_f32_f16_e32 v3, v86
	v_ashrrev_i32_e32 v9, 31, v8
	v_lshl_add_u64 v[8:9], v[8:9], 4, s[4:5]
	v_add_co_u32_e32 v8, vcc, s2, v8
	v_cvt_f32_f16_sdwa v0, v86 dst_sel:DWORD dst_unused:UNUSED_PAD src0_sel:WORD_1
	s_nop 0
	v_addc_co_u32_e32 v9, vcc, 0, v9, vcc
	v_mul_f32_e32 v6, 0xbfb8aa3b, v3
	v_exp_f32_e32 v10, v6
	v_mul_f32_e32 v6, 0xbfb8aa3b, v0
	v_exp_f32_e32 v11, v6
	s_movk_i32 s2, 0x5000
	v_pk_add_f32 v[10:11], v[10:11], 1.0 op_sel_hi:[1,0]
	s_nop 0
	v_div_scale_f32 v6, s[0:1], v11, v11, v0
	s_waitcnt vmcnt(13)
	v_cvt_f32_f16_e32 v12, v88
	v_cvt_f32_f16_sdwa v13, v88 dst_sel:DWORD dst_unused:UNUSED_PAD src0_sel:WORD_1
	v_rcp_f32_e32 v8, v6
	v_pk_fma_f32 v[12:13], v[36:37], v[2:3], v[12:13] op_sel_hi:[1,0,1]
	v_fma_f32 v14, -v6, v8, 1.0
	v_fmac_f32_e32 v8, v14, v8
	v_div_scale_f32 v14, vcc, v0, v11, v0
	v_mul_f32_e32 v15, v14, v8
	v_fma_f32 v32, -v6, v15, v14
	v_fmac_f32_e32 v15, v32, v8
	v_fma_f32 v6, -v6, v15, v14
	v_div_fmas_f32 v6, v6, v8, v15
	v_div_fixup_f32 v11, v6, v11, v0
	v_div_scale_f32 v0, s[0:1], v10, v10, v3
	v_rcp_f32_e32 v6, v0
	s_nop 0
	v_fma_f32 v8, -v0, v6, 1.0
	v_fmac_f32_e32 v6, v8, v6
	v_div_scale_f32 v8, vcc, v3, v10, v3
	v_mul_f32_e32 v14, v8, v6
	v_fma_f32 v15, -v0, v14, v8
	v_fmac_f32_e32 v14, v15, v6
	v_fma_f32 v0, -v0, v14, v8
	v_div_fmas_f32 v0, v0, v6, v14
	v_div_fixup_f32 v10, v0, v10, v3
	v_cvt_f32_f16_e32 v3, v87
	v_cvt_f32_f16_sdwa v0, v87 dst_sel:DWORD dst_unused:UNUSED_PAD src0_sel:WORD_1
	v_pk_mul_f32 v[10:11], v[10:11], v[12:13]
	v_mul_f32_e32 v7, 0xbfb8aa3b, v3
	v_exp_f32_e32 v8, v7
	v_mul_f32_e32 v7, 0xbfb8aa3b, v0
	v_cvt_pk_f16_f32 v6, v10, v11
	v_cvt_f32_f16_e32 v10, v89
	v_cvt_f32_f16_sdwa v11, v89 dst_sel:DWORD dst_unused:UNUSED_PAD src0_sel:WORD_1
	v_exp_f32_e32 v9, v7
	v_pk_fma_f32 v[10:11], v[38:39], v[2:3], v[10:11] op_sel_hi:[1,0,1]
	v_pk_add_f32 v[8:9], v[8:9], 1.0 op_sel_hi:[1,0]
	s_nop 0
	v_div_scale_f32 v7, s[0:1], v9, v9, v0
	v_rcp_f32_e32 v12, v7
	s_nop 0
	v_fma_f32 v13, -v7, v12, 1.0
	v_fmac_f32_e32 v12, v13, v12
	v_div_scale_f32 v13, vcc, v0, v9, v0
	v_mul_f32_e32 v14, v13, v12
	v_fma_f32 v15, -v7, v14, v13
	v_fmac_f32_e32 v14, v15, v12
	v_fma_f32 v7, -v7, v14, v13
	v_div_fmas_f32 v7, v7, v12, v14
	v_div_fixup_f32 v9, v7, v9, v0
	v_div_scale_f32 v0, s[0:1], v8, v8, v3
	v_rcp_f32_e32 v7, v0
	s_nop 0
	v_fma_f32 v12, -v0, v7, 1.0
	v_fmac_f32_e32 v7, v12, v7
	v_div_scale_f32 v12, vcc, v3, v8, v3
	v_mul_f32_e32 v13, v12, v7
	v_fma_f32 v14, -v0, v13, v12
	v_fmac_f32_e32 v13, v14, v7
	v_fma_f32 v0, -v0, v13, v12
	v_div_fmas_f32 v0, v0, v7, v13
	v_div_fixup_f32 v8, v0, v8, v3
	v_pk_mul_f32 v[8:9], v[8:9], v[10:11]
	s_nop 0
	v_cvt_pk_f16_f32 v7, v8, v9
	global_store_dwordx2 v[4:5], v[6:7], off offset:16
	v_mov_b32_e32 v8, v209
	s_waitcnt vmcnt(13)
	v_cvt_f32_f16_e32 v3, v90
	v_ashrrev_i32_e32 v9, 31, v8
	v_lshl_add_u64 v[8:9], v[8:9], 4, s[4:5]
	v_add_co_u32_e32 v8, vcc, s2, v8
	v_cvt_f32_f16_sdwa v0, v90 dst_sel:DWORD dst_unused:UNUSED_PAD src0_sel:WORD_1
	s_nop 0
	v_addc_co_u32_e32 v9, vcc, 0, v9, vcc
	v_mul_f32_e32 v6, 0xbfb8aa3b, v3
	v_exp_f32_e32 v10, v6
	v_mul_f32_e32 v6, 0xbfb8aa3b, v0
	v_exp_f32_e32 v11, v6
	s_waitcnt vmcnt(12)
; DI unsigned pk2(float a, float b) { f2_t v = {a, b}; bf2_t r = __builtin_convertvector(v, bf2_t); return __builtin_bit_cast(unsigned, r); }
; DI float bflo(unsigned u) { return (float)__builtin_bit_cast(bf2_t, u)[0]; }
; DI float bfhi(unsigned u) { return (float)__builtin_bit_cast(bf2_t, u)[1]; }
; DI float siluf_(float x) { return x / (1.f + __expf(-x)); }
; #define NSA_GATE(c_, nb_) sigmoidf_(bf2f(zb[(size_t)qpos[nb_] * ZS + GATEC + (c_) * 8 + head]))
; DI void nsa_item(const Params& p, int l_, int item, char* lds, int dry) {
;     ...
;   for (int nb = 0; nb < 2; ++nb) {
;     const float lt = l[nb] + shx(l[nb], lane, 32);
;     const float sc = ((lt > 0.f) ? 1.f / lt : 0.f) * NSA_GATE(2, nb);
;     u16* zr = zb + (size_t)qpos[nb] * ZS + GC + head * 64;
; #pragma unroll
;     for (int db = 0; db < 2; ++db)
; #pragma unroll
;       for (int a4 = 0; a4 < 4; ++a4) {
;         uint2* gp = (uint2*)(zr + db * 32 + 8 * a4 + 4 * h);
;         const uint2 gv = *gp;
;         const uint2 pv = *((const uint2*)&scr[((nb * 2 + db) * 2 + (a4 >> 1)) * 256] + (a4 & 1));
;         const unsigned o0 = pv.x, o1 = pv.y;
;         uint2 o;
;         o.x = pk2((bflo(o0) + O[db][nb][4 * a4] * sc) * siluf_(bflo(gv.x)),
;                   (bfhi(o0) + O[db][nb][4 * a4 + 1] * sc) * siluf_(bfhi(gv.x)));
;         o.y = pk2((bflo(o1) + O[db][nb][4 * a4 + 2] * sc) * siluf_(bflo(gv.y)),
;                   (bfhi(o1) + O[db][nb][4 * a4 + 3] * sc) * siluf_(bfhi(gv.y)));
;         if (dry) gp = (uint2*)&scr[((nb * 2 + db) * 2 + (a4 >> 1)) * 256] + (a4 & 1);
;         *gp = o;
;       }
	v_cvt_f32_f16_e32 v12, v92
	v_pk_add_f32 v[10:11], v[10:11], 1.0 op_sel_hi:[1,0]
	v_cvt_f32_f16_sdwa v13, v92 dst_sel:DWORD dst_unused:UNUSED_PAD src0_sel:WORD_1
	v_div_scale_f32 v6, s[0:1], v11, v11, v0
	v_rcp_f32_e32 v8, v6
	v_pk_fma_f32 v[12:13], v[40:41], v[2:3], v[12:13] op_sel_hi:[1,0,1]
	v_fma_f32 v14, -v6, v8, 1.0
	v_fmac_f32_e32 v8, v14, v8
	v_div_scale_f32 v14, vcc, v0, v11, v0
	v_mul_f32_e32 v15, v14, v8
	v_fma_f32 v32, -v6, v15, v14
	v_fmac_f32_e32 v15, v32, v8
	v_fma_f32 v6, -v6, v15, v14
	v_div_fmas_f32 v6, v6, v8, v15
	v_div_fixup_f32 v11, v6, v11, v0
	v_div_scale_f32 v0, s[0:1], v10, v10, v3
	v_rcp_f32_e32 v6, v0
	s_nop 0
	v_fma_f32 v8, -v0, v6, 1.0
	v_fmac_f32_e32 v6, v8, v6
	v_div_scale_f32 v8, vcc, v3, v10, v3
	v_mul_f32_e32 v14, v8, v6
	v_fma_f32 v15, -v0, v14, v8
	v_fmac_f32_e32 v14, v15, v6
	v_fma_f32 v0, -v0, v14, v8
	v_div_fmas_f32 v0, v0, v6, v14
	v_div_fixup_f32 v10, v0, v10, v3
	v_cvt_f32_f16_e32 v3, v91
	v_cvt_f32_f16_sdwa v0, v91 dst_sel:DWORD dst_unused:UNUSED_PAD src0_sel:WORD_1
	v_pk_mul_f32 v[10:11], v[10:11], v[12:13]
	v_mul_f32_e32 v7, 0xbfb8aa3b, v3
	v_exp_f32_e32 v8, v7
	v_mul_f32_e32 v7, 0xbfb8aa3b, v0
	v_cvt_pk_f16_f32 v6, v10, v11
	v_cvt_f32_f16_e32 v10, v93
	v_cvt_f32_f16_sdwa v11, v93 dst_sel:DWORD dst_unused:UNUSED_PAD src0_sel:WORD_1
	v_exp_f32_e32 v9, v7
	v_pk_fma_f32 v[10:11], v[42:43], v[2:3], v[10:11] op_sel_hi:[1,0,1]
	v_pk_add_f32 v[8:9], v[8:9], 1.0 op_sel_hi:[1,0]
	s_nop 0
	v_div_scale_f32 v7, s[0:1], v9, v9, v0
	v_rcp_f32_e32 v12, v7
	s_nop 0
	v_fma_f32 v13, -v7, v12, 1.0
	v_fmac_f32_e32 v12, v13, v12
	v_div_scale_f32 v13, vcc, v0, v9, v0
	v_mul_f32_e32 v14, v13, v12
	v_fma_f32 v15, -v7, v14, v13
	v_fmac_f32_e32 v14, v15, v12
	v_fma_f32 v7, -v7, v14, v13
	v_div_fmas_f32 v7, v7, v12, v14
	v_div_fixup_f32 v9, v7, v9, v0
	v_div_scale_f32 v0, s[0:1], v8, v8, v3
	v_rcp_f32_e32 v7, v0
	s_nop 0
	v_fma_f32 v12, -v0, v7, 1.0
	v_fmac_f32_e32 v7, v12, v7
	v_div_scale_f32 v12, vcc, v3, v8, v3
	v_mul_f32_e32 v13, v12, v7
	v_fma_f32 v14, -v0, v13, v12
	v_fmac_f32_e32 v13, v14, v7
	v_fma_f32 v0, -v0, v13, v12
	v_div_fmas_f32 v0, v0, v7, v13
	v_div_fixup_f32 v8, v0, v8, v3
	v_pk_mul_f32 v[8:9], v[8:9], v[10:11]
	s_nop 0
	v_cvt_pk_f16_f32 v7, v8, v9
	global_store_dwordx2 v[4:5], v[6:7], off offset:32
	v_mov_b32_e32 v8, v209
	s_waitcnt vmcnt(12)
	v_cvt_f32_f16_e32 v3, v94
	v_ashrrev_i32_e32 v9, 31, v8
	v_lshl_add_u64 v[8:9], v[8:9], 4, s[4:5]
	v_add_co_u32_e32 v8, vcc, s2, v8
	v_cvt_f32_f16_sdwa v0, v94 dst_sel:DWORD dst_unused:UNUSED_PAD src0_sel:WORD_1
	s_nop 0
	v_addc_co_u32_e32 v9, vcc, 0, v9, vcc
	v_mul_f32_e32 v6, 0xbfb8aa3b, v3
	v_exp_f32_e32 v10, v6
	v_mul_f32_e32 v6, 0xbfb8aa3b, v0
	v_exp_f32_e32 v11, v6
	s_movk_i32 s2, 0x6000
	v_pk_add_f32 v[10:11], v[10:11], 1.0 op_sel_hi:[1,0]
	s_nop 0
	v_div_scale_f32 v6, s[0:1], v11, v11, v0
	s_waitcnt vmcnt(11)
	v_cvt_f32_f16_e32 v12, v96
	v_cvt_f32_f16_sdwa v13, v96 dst_sel:DWORD dst_unused:UNUSED_PAD src0_sel:WORD_1
	v_rcp_f32_e32 v8, v6
	v_pk_fma_f32 v[12:13], v[44:45], v[2:3], v[12:13] op_sel_hi:[1,0,1]
	v_fma_f32 v14, -v6, v8, 1.0
	v_fmac_f32_e32 v8, v14, v8
	v_div_scale_f32 v14, vcc, v0, v11, v0
	v_mul_f32_e32 v15, v14, v8
	v_fma_f32 v32, -v6, v15, v14
	v_fmac_f32_e32 v15, v32, v8
	v_fma_f32 v6, -v6, v15, v14
	v_div_fmas_f32 v6, v6, v8, v15
	v_div_fixup_f32 v11, v6, v11, v0
	v_div_scale_f32 v0, s[0:1], v10, v10, v3
	v_rcp_f32_e32 v6, v0
	s_nop 0
	v_fma_f32 v8, -v0, v6, 1.0
	v_fmac_f32_e32 v6, v8, v6
	v_div_scale_f32 v8, vcc, v3, v10, v3
	v_mul_f32_e32 v14, v8, v6
	v_fma_f32 v15, -v0, v14, v8
	v_fmac_f32_e32 v14, v15, v6
	v_fma_f32 v0, -v0, v14, v8
	v_div_fmas_f32 v0, v0, v6, v14
	v_div_fixup_f32 v10, v0, v10, v3
	v_cvt_f32_f16_e32 v3, v95
	v_cvt_f32_f16_sdwa v0, v95 dst_sel:DWORD dst_unused:UNUSED_PAD src0_sel:WORD_1
	v_pk_mul_f32 v[10:11], v[10:11], v[12:13]
	v_mul_f32_e32 v7, 0xbfb8aa3b, v3
	v_exp_f32_e32 v8, v7
	v_mul_f32_e32 v7, 0xbfb8aa3b, v0
	v_cvt_pk_f16_f32 v6, v10, v11
	v_cvt_f32_f16_e32 v10, v97
	v_cvt_f32_f16_sdwa v11, v97 dst_sel:DWORD dst_unused:UNUSED_PAD src0_sel:WORD_1
	v_exp_f32_e32 v9, v7
	v_pk_fma_f32 v[10:11], v[46:47], v[2:3], v[10:11] op_sel_hi:[1,0,1]
	v_pk_add_f32 v[8:9], v[8:9], 1.0 op_sel_hi:[1,0]
	s_nop 0
	v_div_scale_f32 v7, s[0:1], v9, v9, v0
	v_rcp_f32_e32 v12, v7
	s_nop 0
	v_fma_f32 v13, -v7, v12, 1.0
	v_fmac_f32_e32 v12, v13, v12
	v_div_scale_f32 v13, vcc, v0, v9, v0
	v_mul_f32_e32 v14, v13, v12
	v_fma_f32 v15, -v7, v14, v13
	v_fmac_f32_e32 v14, v15, v12
	v_fma_f32 v7, -v7, v14, v13
	v_div_fmas_f32 v7, v7, v12, v14
	v_div_fixup_f32 v9, v7, v9, v0
	v_div_scale_f32 v0, s[0:1], v8, v8, v3
	v_rcp_f32_e32 v7, v0
	s_nop 0
	v_fma_f32 v12, -v0, v7, 1.0
	v_fmac_f32_e32 v7, v12, v7
	v_div_scale_f32 v12, vcc, v3, v8, v3
	v_mul_f32_e32 v13, v12, v7
	v_fma_f32 v14, -v0, v13, v12
	v_fmac_f32_e32 v13, v14, v7
	v_fma_f32 v0, -v0, v13, v12
	v_div_fmas_f32 v0, v0, v7, v13
	v_div_fixup_f32 v8, v0, v8, v3
	v_pk_mul_f32 v[8:9], v[8:9], v[10:11]
	s_nop 0
	v_cvt_pk_f16_f32 v7, v8, v9
	global_store_dwordx2 v[4:5], v[6:7], off offset:48
	v_mov_b32_e32 v8, v209
	s_waitcnt vmcnt(11)
	v_cvt_f32_f16_e32 v3, v98
	v_ashrrev_i32_e32 v9, 31, v8
	v_lshl_add_u64 v[8:9], v[8:9], 4, s[4:5]
	v_add_co_u32_e32 v8, vcc, s2, v8
	v_cvt_f32_f16_sdwa v0, v98 dst_sel:DWORD dst_unused:UNUSED_PAD src0_sel:WORD_1
	s_nop 0
	v_addc_co_u32_e32 v9, vcc, 0, v9, vcc
	v_mul_f32_e32 v6, 0xbfb8aa3b, v3
	v_exp_f32_e32 v10, v6
	v_mul_f32_e32 v6, 0xbfb8aa3b, v0
	v_exp_f32_e32 v11, v6
	s_waitcnt vmcnt(10)
; DI unsigned pk2(float a, float b) { f2_t v = {a, b}; bf2_t r = __builtin_convertvector(v, bf2_t); return __builtin_bit_cast(unsigned, r); }
; DI float bflo(unsigned u) { return (float)__builtin_bit_cast(bf2_t, u)[0]; }
; DI float bfhi(unsigned u) { return (float)__builtin_bit_cast(bf2_t, u)[1]; }
; DI float siluf_(float x) { return x / (1.f + __expf(-x)); }
; #define NSA_GATE(c_, nb_) sigmoidf_(bf2f(zb[(size_t)qpos[nb_] * ZS + GATEC + (c_) * 8 + head]))
; DI void nsa_item(const Params& p, int l_, int item, char* lds, int dry) {
;     ...
;   for (int nb = 0; nb < 2; ++nb) {
;     const float lt = l[nb] + shx(l[nb], lane, 32);
;     const float sc = ((lt > 0.f) ? 1.f / lt : 0.f) * NSA_GATE(2, nb);
;     u16* zr = zb + (size_t)qpos[nb] * ZS + GC + head * 64;
; #pragma unroll
;     for (int db = 0; db < 2; ++db)
; #pragma unroll
;       for (int a4 = 0; a4 < 4; ++a4) {
;         uint2* gp = (uint2*)(zr + db * 32 + 8 * a4 + 4 * h);
;         const uint2 gv = *gp;
;         const uint2 pv = *((const uint2*)&scr[((nb * 2 + db) * 2 + (a4 >> 1)) * 256] + (a4 & 1));
;         const unsigned o0 = pv.x, o1 = pv.y;
;         uint2 o;
;         o.x = pk2((bflo(o0) + O[db][nb][4 * a4] * sc) * siluf_(bflo(gv.x)),
;                   (bfhi(o0) + O[db][nb][4 * a4 + 1] * sc) * siluf_(bfhi(gv.x)));
;         o.y = pk2((bflo(o1) + O[db][nb][4 * a4 + 2] * sc) * siluf_(bflo(gv.y)),
;                   (bfhi(o1) + O[db][nb][4 * a4 + 3] * sc) * siluf_(bfhi(gv.y)));
;         if (dry) gp = (uint2*)&scr[((nb * 2 + db) * 2 + (a4 >> 1)) * 256] + (a4 & 1);
;         *gp = o;
;       }
	v_cvt_f32_f16_e32 v12, v100
	v_pk_add_f32 v[10:11], v[10:11], 1.0 op_sel_hi:[1,0]
	v_cvt_f32_f16_sdwa v13, v100 dst_sel:DWORD dst_unused:UNUSED_PAD src0_sel:WORD_1
	v_div_scale_f32 v6, s[0:1], v11, v11, v0
	v_rcp_f32_e32 v8, v6
	v_pk_fma_f32 v[12:13], v[16:17], v[2:3], v[12:13] op_sel_hi:[1,0,1]
	v_fma_f32 v14, -v6, v8, 1.0
	v_fmac_f32_e32 v8, v14, v8
	v_div_scale_f32 v14, vcc, v0, v11, v0
	v_mul_f32_e32 v15, v14, v8
	v_fma_f32 v16, -v6, v15, v14
	v_fmac_f32_e32 v15, v16, v8
	v_fma_f32 v6, -v6, v15, v14
	v_div_fmas_f32 v6, v6, v8, v15
	v_div_fixup_f32 v11, v6, v11, v0
	v_div_scale_f32 v0, s[0:1], v10, v10, v3
	v_rcp_f32_e32 v6, v0
	s_nop 0
	v_fma_f32 v8, -v0, v6, 1.0
	v_fmac_f32_e32 v6, v8, v6
	v_div_scale_f32 v8, vcc, v3, v10, v3
	v_mul_f32_e32 v14, v8, v6
	v_fma_f32 v15, -v0, v14, v8
	v_fmac_f32_e32 v14, v15, v6
	v_fma_f32 v0, -v0, v14, v8
	v_div_fmas_f32 v0, v0, v6, v14
	v_div_fixup_f32 v10, v0, v10, v3
	v_cvt_f32_f16_e32 v3, v99
	v_cvt_f32_f16_sdwa v0, v99 dst_sel:DWORD dst_unused:UNUSED_PAD src0_sel:WORD_1
	v_pk_mul_f32 v[10:11], v[10:11], v[12:13]
	v_mul_f32_e32 v7, 0xbfb8aa3b, v3
	v_exp_f32_e32 v8, v7
	v_mul_f32_e32 v7, 0xbfb8aa3b, v0
	v_cvt_pk_f16_f32 v6, v10, v11
	v_cvt_f32_f16_e32 v10, v101
	v_cvt_f32_f16_sdwa v11, v101 dst_sel:DWORD dst_unused:UNUSED_PAD src0_sel:WORD_1
	v_exp_f32_e32 v9, v7
	v_pk_fma_f32 v[10:11], v[18:19], v[2:3], v[10:11] op_sel_hi:[1,0,1]
	v_pk_add_f32 v[8:9], v[8:9], 1.0 op_sel_hi:[1,0]
	s_nop 0
	v_div_scale_f32 v7, s[0:1], v9, v9, v0
	v_rcp_f32_e32 v12, v7
	s_nop 0
	v_fma_f32 v13, -v7, v12, 1.0
	v_fmac_f32_e32 v12, v13, v12
	v_div_scale_f32 v13, vcc, v0, v9, v0
	v_mul_f32_e32 v14, v13, v12
	v_fma_f32 v15, -v7, v14, v13
	v_fmac_f32_e32 v14, v15, v12
	v_fma_f32 v7, -v7, v14, v13
	v_div_fmas_f32 v7, v7, v12, v14
	v_div_fixup_f32 v9, v7, v9, v0
	v_div_scale_f32 v0, s[0:1], v8, v8, v3
	v_rcp_f32_e32 v7, v0
	s_nop 0
	v_fma_f32 v12, -v0, v7, 1.0
	v_fmac_f32_e32 v7, v12, v7
	v_div_scale_f32 v12, vcc, v3, v8, v3
	v_mul_f32_e32 v13, v12, v7
	v_fma_f32 v14, -v0, v13, v12
	v_fmac_f32_e32 v13, v14, v7
	v_fma_f32 v0, -v0, v13, v12
	v_div_fmas_f32 v0, v0, v7, v13
	v_div_fixup_f32 v8, v0, v8, v3
	v_pk_mul_f32 v[8:9], v[8:9], v[10:11]
	s_nop 0
	v_cvt_pk_f16_f32 v7, v8, v9
	global_store_dwordx2 v[4:5], v[6:7], off offset:64
	v_mov_b32_e32 v8, v209
	s_waitcnt vmcnt(10)
	v_cvt_f32_f16_e32 v3, v102
	v_ashrrev_i32_e32 v9, 31, v8
	v_lshl_add_u64 v[8:9], v[8:9], 4, s[4:5]
	v_add_co_u32_e32 v8, vcc, s2, v8
	v_cvt_f32_f16_sdwa v0, v102 dst_sel:DWORD dst_unused:UNUSED_PAD src0_sel:WORD_1
	s_nop 0
	v_addc_co_u32_e32 v9, vcc, 0, v9, vcc
	v_mul_f32_e32 v6, 0xbfb8aa3b, v3
	v_exp_f32_e32 v10, v6
	v_mul_f32_e32 v6, 0xbfb8aa3b, v0
	v_exp_f32_e32 v11, v6
	s_movk_i32 s2, 0x7000
	v_pk_add_f32 v[10:11], v[10:11], 1.0 op_sel_hi:[1,0]
	s_nop 0
	v_div_scale_f32 v6, s[0:1], v11, v11, v0
	s_waitcnt vmcnt(9)
	v_cvt_f32_f16_e32 v12, v104
	v_cvt_f32_f16_sdwa v13, v104 dst_sel:DWORD dst_unused:UNUSED_PAD src0_sel:WORD_1
	v_rcp_f32_e32 v8, v6
	v_pk_fma_f32 v[12:13], v[20:21], v[2:3], v[12:13] op_sel_hi:[1,0,1]
	v_fma_f32 v14, -v6, v8, 1.0
	v_fmac_f32_e32 v8, v14, v8
	v_div_scale_f32 v14, vcc, v0, v11, v0
	v_mul_f32_e32 v15, v14, v8
	v_fma_f32 v16, -v6, v15, v14
	v_fmac_f32_e32 v15, v16, v8
	v_fma_f32 v6, -v6, v15, v14
	v_div_fmas_f32 v6, v6, v8, v15
	v_div_fixup_f32 v11, v6, v11, v0
	v_div_scale_f32 v0, s[0:1], v10, v10, v3
	v_rcp_f32_e32 v6, v0
	s_nop 0
	v_fma_f32 v8, -v0, v6, 1.0
	v_fmac_f32_e32 v6, v8, v6
	v_div_scale_f32 v8, vcc, v3, v10, v3
	v_mul_f32_e32 v14, v8, v6
	v_fma_f32 v15, -v0, v14, v8
	v_fmac_f32_e32 v14, v15, v6
	v_fma_f32 v0, -v0, v14, v8
	v_div_fmas_f32 v0, v0, v6, v14
	v_div_fixup_f32 v10, v0, v10, v3
	v_cvt_f32_f16_e32 v3, v103
	v_cvt_f32_f16_sdwa v0, v103 dst_sel:DWORD dst_unused:UNUSED_PAD src0_sel:WORD_1
	v_pk_mul_f32 v[10:11], v[10:11], v[12:13]
	v_mul_f32_e32 v7, 0xbfb8aa3b, v3
	v_exp_f32_e32 v8, v7
	v_mul_f32_e32 v7, 0xbfb8aa3b, v0
	v_cvt_pk_f16_f32 v6, v10, v11
	v_cvt_f32_f16_e32 v10, v105
	v_cvt_f32_f16_sdwa v11, v105 dst_sel:DWORD dst_unused:UNUSED_PAD src0_sel:WORD_1
	v_exp_f32_e32 v9, v7
	v_pk_fma_f32 v[10:11], v[22:23], v[2:3], v[10:11] op_sel_hi:[1,0,1]
	v_pk_add_f32 v[8:9], v[8:9], 1.0 op_sel_hi:[1,0]
	s_nop 0
	v_div_scale_f32 v7, s[0:1], v9, v9, v0
	v_rcp_f32_e32 v12, v7
	s_nop 0
	v_fma_f32 v13, -v7, v12, 1.0
	v_fmac_f32_e32 v12, v13, v12
	v_div_scale_f32 v13, vcc, v0, v9, v0
	v_mul_f32_e32 v14, v13, v12
	v_fma_f32 v15, -v7, v14, v13
	v_fmac_f32_e32 v14, v15, v12
	v_fma_f32 v7, -v7, v14, v13
	v_div_fmas_f32 v7, v7, v12, v14
	v_div_fixup_f32 v9, v7, v9, v0
	v_div_scale_f32 v0, s[0:1], v8, v8, v3
	v_rcp_f32_e32 v7, v0
	s_nop 0
	v_fma_f32 v12, -v0, v7, 1.0
	v_fmac_f32_e32 v7, v12, v7
	v_div_scale_f32 v12, vcc, v3, v8, v3
	v_mul_f32_e32 v13, v12, v7
	v_fma_f32 v14, -v0, v13, v12
	v_fmac_f32_e32 v13, v14, v7
	v_fma_f32 v0, -v0, v13, v12
	v_div_fmas_f32 v0, v0, v7, v13
	v_div_fixup_f32 v8, v0, v8, v3
	v_pk_mul_f32 v[8:9], v[8:9], v[10:11]
	s_nop 0
	v_cvt_pk_f16_f32 v7, v8, v9
	global_store_dwordx2 v[4:5], v[6:7], off offset:80
	v_mov_b32_e32 v8, v209
	s_waitcnt vmcnt(9)
; DI unsigned pk2(float a, float b) { f2_t v = {a, b}; bf2_t r = __builtin_convertvector(v, bf2_t); return __builtin_bit_cast(unsigned, r); }
; DI float bflo(unsigned u) { return (float)__builtin_bit_cast(bf2_t, u)[0]; }
; DI float bfhi(unsigned u) { return (float)__builtin_bit_cast(bf2_t, u)[1]; }
; DI float siluf_(float x) { return x / (1.f + __expf(-x)); }
; #define NSA_GATE(c_, nb_) sigmoidf_(bf2f(zb[(size_t)qpos[nb_] * ZS + GATEC + (c_) * 8 + head]))
; DI void nsa_item(const Params& p, int l_, int item, char* lds, int dry) {
;     ...
;   for (int nb = 0; nb < 2; ++nb) {
;     const float lt = l[nb] + shx(l[nb], lane, 32);
;     const float sc = ((lt > 0.f) ? 1.f / lt : 0.f) * NSA_GATE(2, nb);
;     u16* zr = zb + (size_t)qpos[nb] * ZS + GC + head * 64;
; #pragma unroll
;     for (int db = 0; db < 2; ++db)
; #pragma unroll
;       for (int a4 = 0; a4 < 4; ++a4) {
;         uint2* gp = (uint2*)(zr + db * 32 + 8 * a4 + 4 * h);
;         const uint2 gv = *gp;
;         const uint2 pv = *((const uint2*)&scr[((nb * 2 + db) * 2 + (a4 >> 1)) * 256] + (a4 & 1));
;         const unsigned o0 = pv.x, o1 = pv.y;
;         uint2 o;
;         o.x = pk2((bflo(o0) + O[db][nb][4 * a4] * sc) * siluf_(bflo(gv.x)),
;                   (bfhi(o0) + O[db][nb][4 * a4 + 1] * sc) * siluf_(bfhi(gv.x)));
;         o.y = pk2((bflo(o1) + O[db][nb][4 * a4 + 2] * sc) * siluf_(bflo(gv.y)),
;                   (bfhi(o1) + O[db][nb][4 * a4 + 3] * sc) * siluf_(bfhi(gv.y)));
;         if (dry) gp = (uint2*)&scr[((nb * 2 + db) * 2 + (a4 >> 1)) * 256] + (a4 & 1);
;         *gp = o;
;       }
	v_cvt_f32_f16_e32 v3, v106
	v_ashrrev_i32_e32 v9, 31, v8
	v_lshl_add_u64 v[8:9], v[8:9], 4, s[4:5]
	v_add_co_u32_e32 v8, vcc, s2, v8
	v_cvt_f32_f16_sdwa v0, v106 dst_sel:DWORD dst_unused:UNUSED_PAD src0_sel:WORD_1
	s_nop 0
	v_addc_co_u32_e32 v9, vcc, 0, v9, vcc
	v_mul_f32_e32 v6, 0xbfb8aa3b, v3
	v_exp_f32_e32 v10, v6
	v_mul_f32_e32 v6, 0xbfb8aa3b, v0
	v_exp_f32_e32 v11, v6
	s_waitcnt vmcnt(8)
	v_cvt_f32_f16_e32 v12, v108
	v_pk_add_f32 v[10:11], v[10:11], 1.0 op_sel_hi:[1,0]
	v_cvt_f32_f16_sdwa v13, v108 dst_sel:DWORD dst_unused:UNUSED_PAD src0_sel:WORD_1
	v_div_scale_f32 v6, s[0:1], v11, v11, v0
	v_rcp_f32_e32 v8, v6
	v_pk_fma_f32 v[12:13], v[24:25], v[2:3], v[12:13] op_sel_hi:[1,0,1]
	v_fma_f32 v14, -v6, v8, 1.0
	v_fmac_f32_e32 v8, v14, v8
	v_div_scale_f32 v14, vcc, v0, v11, v0
	v_mul_f32_e32 v15, v14, v8
	v_fma_f32 v16, -v6, v15, v14
	v_fmac_f32_e32 v15, v16, v8
	v_fma_f32 v6, -v6, v15, v14
	v_div_fmas_f32 v6, v6, v8, v15
	v_div_fixup_f32 v11, v6, v11, v0
	v_div_scale_f32 v0, s[0:1], v10, v10, v3
	v_rcp_f32_e32 v6, v0
	s_nop 0
	v_fma_f32 v8, -v0, v6, 1.0
	v_fmac_f32_e32 v6, v8, v6
	v_div_scale_f32 v8, vcc, v3, v10, v3
	v_mul_f32_e32 v14, v8, v6
	v_fma_f32 v15, -v0, v14, v8
	v_fmac_f32_e32 v14, v15, v6
	v_fma_f32 v0, -v0, v14, v8
	v_div_fmas_f32 v0, v0, v6, v14
	v_div_fixup_f32 v10, v0, v10, v3
	v_cvt_f32_f16_e32 v3, v107
	v_cvt_f32_f16_sdwa v0, v107 dst_sel:DWORD dst_unused:UNUSED_PAD src0_sel:WORD_1
	v_pk_mul_f32 v[10:11], v[10:11], v[12:13]
	v_mul_f32_e32 v7, 0xbfb8aa3b, v3
	v_exp_f32_e32 v8, v7
	v_mul_f32_e32 v7, 0xbfb8aa3b, v0
	v_cvt_pk_f16_f32 v6, v10, v11
	v_cvt_f32_f16_e32 v10, v109
	v_cvt_f32_f16_sdwa v11, v109 dst_sel:DWORD dst_unused:UNUSED_PAD src0_sel:WORD_1
	v_exp_f32_e32 v9, v7
	v_pk_fma_f32 v[10:11], v[26:27], v[2:3], v[10:11] op_sel_hi:[1,0,1]
	v_pk_add_f32 v[8:9], v[8:9], 1.0 op_sel_hi:[1,0]
	s_nop 0
	v_div_scale_f32 v7, s[0:1], v9, v9, v0
	v_rcp_f32_e32 v12, v7
	s_nop 0
	v_fma_f32 v13, -v7, v12, 1.0
	v_fmac_f32_e32 v12, v13, v12
	v_div_scale_f32 v13, vcc, v0, v9, v0
	v_mul_f32_e32 v14, v13, v12
	v_fma_f32 v15, -v7, v14, v13
	v_fmac_f32_e32 v14, v15, v12
	v_fma_f32 v7, -v7, v14, v13
	v_div_fmas_f32 v7, v7, v12, v14
	v_div_fixup_f32 v9, v7, v9, v0
	v_div_scale_f32 v0, s[0:1], v8, v8, v3
	v_rcp_f32_e32 v7, v0
	s_nop 0
	v_fma_f32 v12, -v0, v7, 1.0
	v_fmac_f32_e32 v7, v12, v7
	v_div_scale_f32 v12, vcc, v3, v8, v3
	v_mul_f32_e32 v13, v12, v7
	v_fma_f32 v14, -v0, v13, v12
	v_fmac_f32_e32 v13, v14, v7
	v_fma_f32 v0, -v0, v13, v12
	v_div_fmas_f32 v0, v0, v7, v13
	v_div_fixup_f32 v8, v0, v8, v3
	v_pk_mul_f32 v[8:9], v[8:9], v[10:11]
	s_nop 0
	v_cvt_pk_f16_f32 v7, v8, v9
	global_store_dwordx2 v[4:5], v[6:7], off offset:96
	v_mov_b32_e32 v8, v209
	s_waitcnt vmcnt(8)
	v_cvt_f32_f16_e32 v3, v110
	v_ashrrev_i32_e32 v9, 31, v8
	v_lshl_add_u64 v[8:9], v[8:9], 4, s[4:5]
	v_add_co_u32_e32 v8, vcc, s2, v8
	v_cvt_f32_f16_sdwa v0, v110 dst_sel:DWORD dst_unused:UNUSED_PAD src0_sel:WORD_1
	s_nop 0
	v_addc_co_u32_e32 v9, vcc, 0, v9, vcc
	v_mul_f32_e32 v6, 0xbfb8aa3b, v3
	v_exp_f32_e32 v10, v6
	v_mul_f32_e32 v6, 0xbfb8aa3b, v0
	v_exp_f32_e32 v11, v6
	s_waitcnt vmcnt(7)
	v_cvt_f32_f16_e32 v12, v112
	v_pk_add_f32 v[10:11], v[10:11], 1.0 op_sel_hi:[1,0]
	v_cvt_f32_f16_sdwa v13, v112 dst_sel:DWORD dst_unused:UNUSED_PAD src0_sel:WORD_1
	v_div_scale_f32 v6, s[0:1], v11, v11, v0
	v_rcp_f32_e32 v8, v6
	v_pk_fma_f32 v[12:13], v[28:29], v[2:3], v[12:13] op_sel_hi:[1,0,1]
	v_fma_f32 v14, -v6, v8, 1.0
	v_fmac_f32_e32 v8, v14, v8
	v_div_scale_f32 v14, vcc, v0, v11, v0
	v_mul_f32_e32 v15, v14, v8
	v_fma_f32 v16, -v6, v15, v14
	v_fmac_f32_e32 v15, v16, v8
	v_fma_f32 v6, -v6, v15, v14
	v_div_fmas_f32 v6, v6, v8, v15
	v_div_fixup_f32 v11, v6, v11, v0
	v_div_scale_f32 v0, s[0:1], v10, v10, v3
	v_rcp_f32_e32 v6, v0
	s_nop 0
	v_fma_f32 v8, -v0, v6, 1.0
	v_fmac_f32_e32 v6, v8, v6
	v_div_scale_f32 v8, vcc, v3, v10, v3
	v_mul_f32_e32 v14, v8, v6
	v_fma_f32 v15, -v0, v14, v8
	v_fmac_f32_e32 v14, v15, v6
	v_fma_f32 v0, -v0, v14, v8
	v_div_fmas_f32 v0, v0, v6, v14
	v_div_fixup_f32 v10, v0, v10, v3
	v_cvt_f32_f16_sdwa v0, v111 dst_sel:DWORD dst_unused:UNUSED_PAD src0_sel:WORD_1
	v_cvt_f32_f16_e32 v7, v111
	v_pk_mul_f32 v[10:11], v[10:11], v[12:13]
	v_mul_f32_e32 v3, 0xbfb8aa3b, v7
	v_cvt_pk_f16_f32 v6, v10, v11
	v_cvt_f32_f16_e32 v10, v113
	v_cvt_f32_f16_sdwa v11, v113 dst_sel:DWORD dst_unused:UNUSED_PAD src0_sel:WORD_1
	v_mul_f32_e32 v9, 0xbfb8aa3b, v0
	v_exp_f32_e32 v8, v3
	v_exp_f32_e32 v9, v9
	v_pk_fma_f32 v[2:3], v[30:31], v[2:3], v[10:11] op_sel_hi:[1,0,1]
	v_pk_add_f32 v[8:9], v[8:9], 1.0 op_sel_hi:[1,0]
	s_nop 0
	v_div_scale_f32 v10, s[0:1], v9, v9, v0
	v_rcp_f32_e32 v11, v10
	s_nop 0
	v_fma_f32 v12, -v10, v11, 1.0
	v_fmac_f32_e32 v11, v12, v11
	v_div_scale_f32 v12, vcc, v0, v9, v0
	v_mul_f32_e32 v13, v12, v11
	v_fma_f32 v14, -v10, v13, v12
	v_fmac_f32_e32 v13, v14, v11
	v_fma_f32 v10, -v10, v13, v12
	v_div_fmas_f32 v10, v10, v11, v13
	v_div_fixup_f32 v9, v10, v9, v0
	v_div_scale_f32 v0, s[0:1], v8, v8, v7
	v_rcp_f32_e32 v10, v0
	s_mov_b64 s[0:1], 0
	v_fma_f32 v11, -v0, v10, 1.0
	v_fmac_f32_e32 v10, v11, v10
	v_div_scale_f32 v11, vcc, v7, v8, v7
	v_mul_f32_e32 v12, v11, v10
	v_fma_f32 v13, -v0, v12, v11
	v_fmac_f32_e32 v12, v13, v10
	v_fma_f32 v0, -v0, v12, v11
	v_div_fmas_f32 v0, v0, v10, v12
	v_div_fixup_f32 v8, v0, v8, v7
	v_pk_mul_f32 v[2:3], v[8:9], v[2:3]
	s_nop 0
	v_cvt_pk_f16_f32 v7, v2, v3
	global_store_dwordx2 v[4:5], v[6:7], off offset:112
	s_branch .LBB0_630
